# v18 + VM2 K-fragment LDS reads one per PV gap + back-edge rotation of the attention loops (no wait edits, no numerics change)
# speedup vs baseline: 1.0094x; 1.0021x over previous
.LBB0_863:
	v_mfma_f32_32x32x16_bf16 v[112:127], v[100:103], v[218:221], 0
	v_lshl_add_u32 v206, s89, 1, v168
	ds_read_b64_tr_b16 v[194:195], v206 offset:24576
	ds_read_b64_tr_b16 v[196:197], v206 offset:25088
	v_add_f32_e32 v108, v80, v81
	v_add_f32_e32 v108, v82, v108
	v_add_f32_e32 v108, v83, v108
	v_add_f32_e32 v108, v84, v108
	v_add_f32_e32 v108, v85, v108
	v_cvt_pk_bf16_f32 v156, v80, v81
	v_cvt_pk_bf16_f32 v157, v82, v83
	ds_read_b64_tr_b16 v[80:81], v206 offset:28672
	ds_read_b64_tr_b16 v[82:83], v206 offset:29184
	v_add_f32_e32 v104, v86, v108
	v_add_f32_e32 v104, v87, v104
	v_add_f32_e32 v104, v88, v104
	v_add_f32_e32 v144, v89, v104
	v_mfma_f32_32x32x16_bf16 v[96:111], v[96:99], v[218:221], 0
	v_cvt_pk_bf16_f32 v158, v84, v85
	v_cvt_pk_bf16_f32 v159, v86, v87
	ds_read_b64_tr_b16 v[84:85], v206 offset:25600
	ds_read_b64_tr_b16 v[86:87], v206 offset:26112
	v_add_f32_e32 v144, v90, v144
	v_add_f32_e32 v144, v91, v144
	v_add_f32_e32 v144, v92, v144
	v_add_f32_e32 v144, v93, v144
	v_cvt_pk_bf16_f32 v152, v88, v89
	v_cvt_pk_bf16_f32 v153, v90, v91
	v_mfma_f32_32x32x16_bf16 v[112:127], v[164:167], v[222:225], v[112:127]
	ds_read_b64_tr_b16 v[88:89], v206 offset:29696
	ds_read_b64_tr_b16 v[90:91], v206 offset:30208
	v_add_f32_e32 v144, v94, v144
	v_add_f32_e32 v144, v95, v144
	v_add_f32_e32 v144, v64, v144
	v_add_f32_e32 v144, v65, v144
	v_mfma_f32_32x32x16_bf16 v[96:111], v[160:163], v[222:225], v[96:111]
	v_cvt_pk_bf16_f32 v154, v92, v93
	v_cvt_pk_bf16_f32 v155, v94, v95
	ds_read_b64_tr_b16 v[92:93], v206 offset:26624
	ds_read_b64_tr_b16 v[94:95], v206 offset:27136
	v_add_f32_e32 v144, v66, v144
	v_add_f32_e32 v144, v67, v144
	v_add_f32_e32 v144, v68, v144
	v_add_f32_e32 v144, v69, v144
	v_cvt_pk_bf16_f32 v148, v64, v65
	v_cvt_pk_bf16_f32 v149, v66, v67
	v_mfma_f32_32x32x16_bf16 v[112:127], v[140:143], v[226:229], v[112:127]
	ds_read_b64_tr_b16 v[198:199], v206 offset:30720
	ds_read_b64_tr_b16 v[200:201], v206 offset:31232
	v_add_f32_e32 v140, v70, v144
	v_add_f32_e32 v140, v71, v140
	v_add_f32_e32 v140, v72, v140
	v_add_f32_e32 v140, v73, v140
	v_mfma_f32_32x32x16_bf16 v[96:111], v[136:139], v[226:229], v[96:111]
	v_cvt_pk_bf16_f32 v150, v68, v69
	v_cvt_pk_bf16_f32 v151, v70, v71
	ds_read_b64_tr_b16 v[202:203], v206 offset:27648
	ds_read_b64_tr_b16 v[204:205], v206 offset:28160
	v_add_f32_e32 v68, v74, v140
	v_add_f32_e32 v68, v75, v68
	v_add_f32_e32 v68, v76, v68
	v_add_f32_e32 v68, v77, v68
	v_cvt_pk_bf16_f32 v144, v72, v73
	v_cvt_pk_bf16_f32 v145, v74, v75
	v_mfma_f32_32x32x16_bf16 v[112:127], v[132:135], v[230:233], v[112:127]
	ds_read_b64_tr_b16 v[72:73], v206 offset:31744
	ds_read_b64_tr_b16 v[74:75], v206 offset:32256
	v_add_f32_e32 v68, v78, v68
	v_add_f32_e32 v68, v79, v68
	v_add_f32_e32 v68, 0, v68
	v_cvt_pk_bf16_f32 v146, v76, v77
	v_mfma_f32_32x32x16_bf16 v[96:111], v[128:131], v[230:233], v[96:111]
	v_cvt_pk_bf16_f32 v147, v78, v79
	s_add_i32 s88, s87, s35
	v_lshl_add_u64 v[64:65], v[180:181], 0, s[54:55]
	s_mov_b32 s89, m0
	s_mov_b32 m0, s88
	s_nop 0
	global_load_lds_dwordx4 v[64:65], off
	s_mov_b32 m0, s89
	s_lshl_b32 s88, s86, 1
	v_lshl_add_u64 v[64:65], v[178:179], 0, s[54:55]
	s_add_i32 s88, s88, s16
	s_mov_b32 s89, m0
	s_mov_b32 m0, s88
	s_nop 0
	global_load_lds_dwordx4 v[64:65], off
	s_mov_b32 m0, s89
	v_lshl_add_u64 v[64:65], v[176:177], 0, s[54:55]
	s_addk_i32 s88, 0x2000
	s_mov_b32 s89, m0
	s_mov_b32 m0, s88
	s_nop 0
	global_load_lds_dwordx4 v[64:65], off
	s_mov_b32 m0, s89
	v_add_f32_e32 v193, v193, v68
	v_add_u32_e32 v242, s86, v234
	v_add_u32_e32 v243, s86, v235
	v_add_u32_e32 v244, s86, v236
	v_add_u32_e32 v245, s86, v237
	s_waitcnt lgkmcnt(12)
	v_mfma_f32_32x32x16_bf16 v[48:63], v[156:159], v[194:197], v[48:63]
	ds_read_b64_tr_b16 v[76:77], v206 offset:32768
	ds_read_b64_tr_b16 v[78:79], v206 offset:33280
	v_exp_f32_e32 v112, v112
	v_exp_f32_e32 v113, v113
	ds_read_b128 v[68:71], v242
	v_mfma_f32_32x32x16_bf16 v[32:47], v[156:159], v[80:83], v[32:47]
	ds_read_b64_tr_b16 v[194:195], v206 offset:36864
	ds_read_b64_tr_b16 v[196:197], v206 offset:37376
	v_exp_f32_e32 v114, v114
	v_exp_f32_e32 v115, v115
	ds_read_b128 v[64:67], v242 offset:4096
	s_waitcnt lgkmcnt(14)
	v_mfma_f32_32x32x16_bf16 v[48:63], v[152:155], v[84:87], v[48:63]
	ds_read_b64_tr_b16 v[80:81], v206 offset:33792
	ds_read_b64_tr_b16 v[82:83], v206 offset:34304
	v_exp_f32_e32 v116, v116
	v_exp_f32_e32 v117, v117
	ds_read_b128 v[164:167], v243
	v_mfma_f32_32x32x16_bf16 v[32:47], v[152:155], v[88:91], v[32:47]
	ds_read_b64_tr_b16 v[84:85], v206 offset:37888
	ds_read_b64_tr_b16 v[86:87], v206 offset:38400
	v_exp_f32_e32 v118, v118
	v_exp_f32_e32 v119, v119
	ds_read_b128 v[140:143], v243 offset:4096
	s_waitcnt lgkmcnt(14)
	v_mfma_f32_32x32x16_bf16 v[48:63], v[148:151], v[92:95], v[48:63]
	ds_read_b64_tr_b16 v[88:89], v206 offset:34816
	ds_read_b64_tr_b16 v[90:91], v206 offset:35328
	v_exp_f32_e32 v120, v120
	v_exp_f32_e32 v121, v121
	ds_read_b128 v[160:163], v244
	v_mfma_f32_32x32x16_bf16 v[32:47], v[148:151], v[198:201], v[32:47]
	ds_read_b64_tr_b16 v[92:93], v206 offset:38912
	ds_read_b64_tr_b16 v[94:95], v206 offset:39424
	v_exp_f32_e32 v122, v122
	v_exp_f32_e32 v123, v123
	ds_read_b128 v[132:135], v244 offset:4096
	s_waitcnt lgkmcnt(14)
	v_mfma_f32_32x32x16_bf16 v[48:63], v[144:147], v[202:205], v[48:63]
	ds_read_b64_tr_b16 v[198:199], v206 offset:35840
	ds_read_b64_tr_b16 v[200:201], v206 offset:36352
	v_exp_f32_e32 v124, v124
	v_exp_f32_e32 v125, v125
	ds_read_b128 v[136:139], v245
	v_mfma_f32_32x32x16_bf16 v[32:47], v[144:147], v[72:75], v[32:47]
	ds_read_b64_tr_b16 v[202:203], v206 offset:39936
	ds_read_b64_tr_b16 v[204:205], v206 offset:40448
	v_exp_f32_e32 v126, v126
	v_exp_f32_e32 v127, v127
	ds_read_b128 v[128:131], v245 offset:4096
	s_waitcnt lgkmcnt(14)
	v_mfma_f32_32x32x16_bf16 v[16:31], v[156:159], v[76:79], v[16:31]
	v_exp_f32_e32 v96, v96
	v_exp_f32_e32 v97, v97
	v_mfma_f32_32x32x16_bf16 v[0:15], v[156:159], v[194:197], v[0:15]
	v_exp_f32_e32 v98, v98
	v_exp_f32_e32 v99, v99
	v_mfma_f32_32x32x16_bf16 v[16:31], v[152:155], v[80:83], v[16:31]
	v_exp_f32_e32 v100, v100
	v_exp_f32_e32 v101, v101
	s_waitcnt lgkmcnt(12)
	v_mfma_f32_32x32x16_bf16 v[0:15], v[152:155], v[84:87], v[0:15]
	v_exp_f32_e32 v102, v102
	v_exp_f32_e32 v103, v103
	s_waitcnt lgkmcnt(8)
	v_mfma_f32_32x32x16_bf16 v[16:31], v[148:151], v[88:91], v[16:31]
	v_exp_f32_e32 v104, v104
	v_exp_f32_e32 v105, v105
	s_waitcnt lgkmcnt(4)
	v_mfma_f32_32x32x16_bf16 v[0:15], v[148:151], v[92:95], v[0:15]
	v_exp_f32_e32 v106, v106
	v_exp_f32_e32 v107, v107
	s_waitcnt lgkmcnt(2)
	v_mfma_f32_32x32x16_bf16 v[16:31], v[144:147], v[198:201], v[16:31]
	v_exp_f32_e32 v108, v108
	v_exp_f32_e32 v109, v109
	s_waitcnt lgkmcnt(0)
	v_mfma_f32_32x32x16_bf16 v[0:15], v[144:147], v[202:205], v[0:15]
	v_exp_f32_e32 v110, v110
	v_exp_f32_e32 v111, v111
	s_waitcnt vmcnt(3) lgkmcnt(0)
	s_barrier
	v_mfma_f32_32x32x16_bf16 v[80:95], v[68:71], v[218:221], 0
	s_add_i32 s88, s86, 0x2000
	s_cmpk_lg_i32 s86, 0x4000
	s_cselect_b32 s88, s88, 0
	v_lshl_add_u32 v206, s87, 1, v168
	ds_read_b64_tr_b16 v[194:195], v206 offset:24576
	ds_read_b64_tr_b16 v[196:197], v206 offset:25088
	v_add_f32_e32 v76, v112, v113
	v_add_f32_e32 v76, v114, v76
	v_add_f32_e32 v76, v115, v76
	v_add_f32_e32 v76, v116, v76
	v_add_f32_e32 v76, v117, v76
	v_cvt_pk_bf16_f32 v156, v112, v113
	v_cvt_pk_bf16_f32 v157, v114, v115
	ds_read_b64_tr_b16 v[112:113], v206 offset:28672
	ds_read_b64_tr_b16 v[114:115], v206 offset:29184
	v_add_f32_e32 v72, v118, v76
	v_add_f32_e32 v72, v119, v72
	v_add_f32_e32 v72, v120, v72
	v_add_f32_e32 v144, v121, v72
	v_mfma_f32_32x32x16_bf16 v[64:79], v[64:67], v[218:221], 0
	v_cvt_pk_bf16_f32 v158, v116, v117
	v_cvt_pk_bf16_f32 v159, v118, v119
	ds_read_b64_tr_b16 v[116:117], v206 offset:25600
	ds_read_b64_tr_b16 v[118:119], v206 offset:26112
	v_add_f32_e32 v144, v122, v144
	v_add_f32_e32 v144, v123, v144
	v_add_f32_e32 v144, v124, v144
	v_add_f32_e32 v144, v125, v144
	v_mfma_f32_32x32x16_bf16 v[80:95], v[164:167], v[222:225], v[80:95]
	v_cvt_pk_bf16_f32 v152, v120, v121
	v_cvt_pk_bf16_f32 v153, v122, v123
	ds_read_b64_tr_b16 v[120:121], v206 offset:29696
	ds_read_b64_tr_b16 v[122:123], v206 offset:30208
	v_add_f32_e32 v144, v126, v144
	v_add_f32_e32 v144, v127, v144
	v_add_f32_e32 v144, v96, v144
	v_add_f32_e32 v144, v97, v144
	v_mfma_f32_32x32x16_bf16 v[64:79], v[140:143], v[222:225], v[64:79]
	v_cvt_pk_bf16_f32 v154, v124, v125
	v_cvt_pk_bf16_f32 v155, v126, v127
	ds_read_b64_tr_b16 v[124:125], v206 offset:26624
	ds_read_b64_tr_b16 v[126:127], v206 offset:27136
	v_add_f32_e32 v144, v98, v144
	v_add_f32_e32 v144, v99, v144
	v_add_f32_e32 v144, v100, v144
	v_add_f32_e32 v144, v101, v144
	v_mfma_f32_32x32x16_bf16 v[80:95], v[160:163], v[226:229], v[80:95]
	v_cvt_pk_bf16_f32 v148, v96, v97
	v_cvt_pk_bf16_f32 v149, v98, v99
	ds_read_b64_tr_b16 v[198:199], v206 offset:30720
	ds_read_b64_tr_b16 v[200:201], v206 offset:31232
	v_add_f32_e32 v140, v102, v144
	v_add_f32_e32 v140, v103, v140
	v_add_f32_e32 v140, v104, v140
	v_add_f32_e32 v140, v105, v140
	v_mfma_f32_32x32x16_bf16 v[64:79], v[132:135], v[226:229], v[64:79]
	v_cvt_pk_bf16_f32 v150, v100, v101
	v_cvt_pk_bf16_f32 v151, v102, v103
	ds_read_b64_tr_b16 v[202:203], v206 offset:27648
	ds_read_b64_tr_b16 v[204:205], v206 offset:28160
	v_add_f32_e32 v100, v106, v140
	v_add_f32_e32 v100, v107, v100
	v_add_f32_e32 v100, v108, v100
	v_add_f32_e32 v100, v109, v100
	v_mfma_f32_32x32x16_bf16 v[80:95], v[136:139], v[230:233], v[80:95]
	v_cvt_pk_bf16_f32 v144, v104, v105
	v_cvt_pk_bf16_f32 v145, v106, v107
	ds_read_b64_tr_b16 v[104:105], v206 offset:31744
	ds_read_b64_tr_b16 v[106:107], v206 offset:32256
	v_add_f32_e32 v100, v110, v100
	v_add_f32_e32 v100, v111, v100
	v_add_f32_e32 v100, 0, v100
	v_cvt_pk_bf16_f32 v146, v108, v109
	v_mfma_f32_32x32x16_bf16 v[64:79], v[128:131], v[230:233], v[64:79]
	v_cvt_pk_bf16_f32 v147, v110, v111
	s_add_i32 s87, s86, s35
	s_mov_b32 s89, m0
	s_mov_b32 m0, s87
	s_nop 0
	global_load_lds_dwordx4 v[180:181], off
	s_mov_b32 m0, s89
	s_lshl_b32 s87, s88, 1
	s_add_i32 s87, s87, s16
	s_mov_b32 s89, m0
	s_mov_b32 m0, s87
	s_nop 0
	global_load_lds_dwordx4 v[178:179], off
	s_mov_b32 m0, s89
	s_addk_i32 s87, 0x2000
	s_mov_b32 s89, m0
	s_mov_b32 m0, s87
	s_nop 0
	global_load_lds_dwordx4 v[176:177], off
	s_mov_b32 m0, s89
	v_add_f32_e32 v193, v193, v100
	v_add_u32_e32 v242, s88, v234
	v_add_u32_e32 v243, s88, v235
	v_add_u32_e32 v244, s88, v236
	v_add_u32_e32 v245, s88, v237
	s_waitcnt lgkmcnt(12)
	v_mfma_f32_32x32x16_bf16 v[48:63], v[156:159], v[194:197], v[48:63]
	ds_read_b64_tr_b16 v[108:109], v206 offset:32768
	ds_read_b64_tr_b16 v[110:111], v206 offset:33280
	v_exp_f32_e32 v80, v80
	v_exp_f32_e32 v81, v81
	ds_read_b128 v[100:103], v242
	v_mfma_f32_32x32x16_bf16 v[32:47], v[156:159], v[112:115], v[32:47]
	ds_read_b64_tr_b16 v[194:195], v206 offset:36864
	ds_read_b64_tr_b16 v[196:197], v206 offset:37376
	v_exp_f32_e32 v82, v82
	v_exp_f32_e32 v83, v83
	ds_read_b128 v[96:99], v242 offset:4096
	s_waitcnt lgkmcnt(14)
	v_mfma_f32_32x32x16_bf16 v[48:63], v[152:155], v[116:119], v[48:63]
	ds_read_b64_tr_b16 v[112:113], v206 offset:33792
	ds_read_b64_tr_b16 v[114:115], v206 offset:34304
	v_exp_f32_e32 v84, v84
	v_exp_f32_e32 v85, v85
	ds_read_b128 v[164:167], v243
	v_mfma_f32_32x32x16_bf16 v[32:47], v[152:155], v[120:123], v[32:47]
	ds_read_b64_tr_b16 v[116:117], v206 offset:37888
	ds_read_b64_tr_b16 v[118:119], v206 offset:38400
	v_exp_f32_e32 v86, v86
	v_exp_f32_e32 v87, v87
	ds_read_b128 v[160:163], v243 offset:4096
	s_waitcnt lgkmcnt(14)
	v_mfma_f32_32x32x16_bf16 v[48:63], v[148:151], v[124:127], v[48:63]
	ds_read_b64_tr_b16 v[120:121], v206 offset:34816
	ds_read_b64_tr_b16 v[122:123], v206 offset:35328
	v_exp_f32_e32 v88, v88
	v_exp_f32_e32 v89, v89
	ds_read_b128 v[140:143], v244
	v_mfma_f32_32x32x16_bf16 v[32:47], v[148:151], v[198:201], v[32:47]
	ds_read_b64_tr_b16 v[124:125], v206 offset:38912
	ds_read_b64_tr_b16 v[126:127], v206 offset:39424
	v_exp_f32_e32 v90, v90
	v_exp_f32_e32 v91, v91
	ds_read_b128 v[136:139], v244 offset:4096
	s_waitcnt lgkmcnt(14)
	v_mfma_f32_32x32x16_bf16 v[48:63], v[144:147], v[202:205], v[48:63]
	ds_read_b64_tr_b16 v[198:199], v206 offset:35840
	ds_read_b64_tr_b16 v[200:201], v206 offset:36352
	v_exp_f32_e32 v92, v92
	v_exp_f32_e32 v93, v93
	ds_read_b128 v[132:135], v245
	v_mfma_f32_32x32x16_bf16 v[32:47], v[144:147], v[104:107], v[32:47]
	ds_read_b64_tr_b16 v[202:203], v206 offset:39936
	ds_read_b64_tr_b16 v[204:205], v206 offset:40448
	v_exp_f32_e32 v94, v94
	v_exp_f32_e32 v95, v95
	ds_read_b128 v[128:131], v245 offset:4096
	s_waitcnt lgkmcnt(14)
; #define WAIT_BAR(N) asm volatile("s_waitcnt vmcnt(" #N ") lgkmcnt(0)\n\ts_barrier":::"memory")
;   #define RESC() do{ if(!NOMAX&&resc){ asm volatile("s_waitcnt lgkmcnt(0)":::"memory"); \
;       _Pragma("unroll") for(int d_=0;d_<2*VM;++d_) _Pragma("unroll") for(int r=0;r<16;++r)o[d_][r]*=wsf[crow(r,hi)]; } }while(0)
;   #define ROT() do{sl_prev=sl_cur;sl_cur=sl_next;sl_next=(sl_next==(NSLOT-1)*SLOTB)?0:sl_next+SLOTB;}while(0)
;   #define ENDW(tt) do{ if((tt)+3<NT){ if constexpr(VM==2){WAIT_BAR(3);}else{WAIT_BAR(2);} } else if((tt)+2<NT){ if constexpr(VM==2){WAIT_BAR(2);}else{WAIT_BAR(1);} } else {WAIT_BAR(0);} }while(0)
; template<int THRL,int VM,bool NOMAX> __device__ __forceinline__ void attn_unit(const bf16*Qb,const bf16*__restrict__ Kh,const bf16*__restrict__ Vh,bf16*Ob,const int NT,const int sp,float*wscr,char*shm){
;     ...
;   int t=1;
;   for(;t+5<NT;t+=2){
;     STEP(pB0,pB1,pA0,pA1,t,true,true,true);     if constexpr(VM==2){WAIT_BAR(3);}else{WAIT_BAR(2);} RESC(); ROT();
;     STEP(pA0,pA1,pB0,pB1,t+1,true,true,true);   if constexpr(VM==2){WAIT_BAR(3);}else{WAIT_BAR(2);} RESC(); ROT();
;   }
;     ...
;   for(;t+1<NT;t+=2){
;     STEP(pB0,pB1,pA0,pA1,t,(t+3<NT),(t+1<NT),(t+1<NT));       ENDW(t);   RESC(); ROT();
;     STEP(pA0,pA1,pB0,pB1,t+1,(t+4<NT),(t+2<NT),(t+2<NT));     ENDW(t+1); RESC(); ROT();
	v_mfma_f32_32x32x16_bf16 v[16:31], v[156:159], v[108:111], v[16:31]
	v_exp_f32_e32 v64, v64
	v_exp_f32_e32 v65, v65
	v_mfma_f32_32x32x16_bf16 v[0:15], v[156:159], v[194:197], v[0:15]
	v_exp_f32_e32 v66, v66
	v_exp_f32_e32 v67, v67
	v_mfma_f32_32x32x16_bf16 v[16:31], v[152:155], v[112:115], v[16:31]
	v_exp_f32_e32 v68, v68
	v_exp_f32_e32 v69, v69
	s_waitcnt lgkmcnt(12)
	v_mfma_f32_32x32x16_bf16 v[0:15], v[152:155], v[116:119], v[0:15]
	v_exp_f32_e32 v70, v70
	v_exp_f32_e32 v71, v71
	s_waitcnt lgkmcnt(8)
	v_mfma_f32_32x32x16_bf16 v[16:31], v[148:151], v[120:123], v[16:31]
	v_exp_f32_e32 v72, v72
	v_exp_f32_e32 v73, v73
	s_waitcnt lgkmcnt(4)
	v_mfma_f32_32x32x16_bf16 v[0:15], v[148:151], v[124:127], v[0:15]
	v_exp_f32_e32 v74, v74
	v_exp_f32_e32 v75, v75
	s_waitcnt lgkmcnt(2)
	v_mfma_f32_32x32x16_bf16 v[16:31], v[144:147], v[198:201], v[16:31]
	v_exp_f32_e32 v76, v76
	v_exp_f32_e32 v77, v77
	s_waitcnt lgkmcnt(0)
	v_mfma_f32_32x32x16_bf16 v[0:15], v[144:147], v[202:205], v[0:15]
	v_exp_f32_e32 v78, v78
	v_exp_f32_e32 v79, v79
	s_add_i32 s90, s88, 0x2000
	s_cmpk_lg_i32 s88, 0x4000
	s_mov_b32 s89, s86
	s_cselect_b32 s86, s90, 0
	s_add_i32 s85, s85, 2
	v_lshl_add_u64 v[176:177], v[176:177], 0, s[56:57]
	v_lshl_add_u64 v[178:179], v[178:179], 0, s[56:57]
	v_lshl_add_u64 v[180:181], v[180:181], 0, s[56:57]
	s_mov_b32 s87, s88
	s_cmpk_lt_u32 s85, 0x79
	s_waitcnt vmcnt(3) lgkmcnt(0)
	s_barrier
	s_cbranch_scc1 .LBB0_863
	s_and_b32 s34, s34, 0x3fffffc0
	s_lshl_b32 s34, s34, 2
	s_add_i32 s34, s34, 0
	s_add_i32 s34, s34, 0x12000
	s_cmp_lg_u32 0, -1
	s_cselect_b32 s85, 0, 0
	s_add_i32 s86, s85, 0x6000
	v_add_u32_e32 v104, s86, v191
	v_add3_u32 v176, v104, v190, v192
	v_add_u32_e32 v177, 0x6000, v168
	ds_read_b64_tr_b16 v[178:179], v168 offset:57344
	ds_read_b64_tr_b16 v[180:181], v168 offset:57856
	v_add_f32_e32 v108, v80, v81
	ds_read_b128 v[104:107], v188
	v_add_f32_e32 v108, v82, v108
	v_add_f32_e32 v108, v83, v108
	v_add_f32_e32 v108, v84, v108
	v_add_f32_e32 v108, v85, v108
	v_cvt_pk_bf16_f32 v156, v80, v81
	v_cvt_pk_bf16_f32 v157, v82, v83
	s_waitcnt lgkmcnt(0)
	v_mfma_f32_32x32x16_bf16 v[112:127], v[100:103], v[104:107], 0
	ds_read_b64_tr_b16 v[80:81], v168 offset:61440
	ds_read_b64_tr_b16 v[82:83], v168 offset:61952
	ds_read_b128 v[100:103], v188
	v_add_f32_e32 v104, v86, v108
	v_add_f32_e32 v104, v87, v104
	v_add_f32_e32 v104, v88, v104
	v_add_f32_e32 v144, v89, v104
	v_cvt_pk_bf16_f32 v158, v84, v85
	v_cvt_pk_bf16_f32 v159, v86, v87
	s_waitcnt lgkmcnt(0)
	v_mfma_f32_32x32x16_bf16 v[96:111], v[96:99], v[100:103], 0
	ds_read_b64_tr_b16 v[84:85], v168 offset:58368
	ds_read_b64_tr_b16 v[86:87], v168 offset:58880
	ds_read_b128 v[194:197], v188 offset:1024
	v_add_f32_e32 v144, v90, v144
	v_add_f32_e32 v144, v91, v144
	v_add_f32_e32 v144, v92, v144
	v_add_f32_e32 v144, v93, v144
	v_cvt_pk_bf16_f32 v152, v88, v89
	v_cvt_pk_bf16_f32 v153, v90, v91
	s_waitcnt lgkmcnt(0)
	v_mfma_f32_32x32x16_bf16 v[112:127], v[164:167], v[194:197], v[112:127]
	ds_read_b64_tr_b16 v[88:89], v168 offset:62464
	ds_read_b64_tr_b16 v[90:91], v168 offset:62976
	ds_read_b128 v[164:167], v188 offset:1024
	v_add_f32_e32 v144, v94, v144
	v_add_f32_e32 v144, v95, v144
	v_add_f32_e32 v144, v64, v144
	v_add_f32_e32 v144, v65, v144
	v_cvt_pk_bf16_f32 v154, v92, v93
	v_cvt_pk_bf16_f32 v155, v94, v95
	s_waitcnt lgkmcnt(0)
	v_mfma_f32_32x32x16_bf16 v[96:111], v[160:163], v[164:167], v[96:111]
	ds_read_b64_tr_b16 v[194:195], v168 offset:59392
	ds_read_b64_tr_b16 v[196:197], v168 offset:59904
	ds_read_b128 v[92:95], v188 offset:2048
	v_add_f32_e32 v144, v66, v144
	v_add_f32_e32 v144, v67, v144
	v_add_f32_e32 v144, v68, v144
	v_add_f32_e32 v144, v69, v144
	v_cvt_pk_bf16_f32 v148, v64, v65
	v_cvt_pk_bf16_f32 v149, v66, v67
	s_waitcnt lgkmcnt(0)
	v_mfma_f32_32x32x16_bf16 v[112:127], v[140:143], v[92:95], v[112:127]
	ds_read_b64_tr_b16 v[140:141], v168 offset:63488
	ds_read_b64_tr_b16 v[142:143], v168 offset:64000
	ds_read_b128 v[64:67], v188 offset:2048
	v_add_f32_e32 v92, v70, v144
	v_add_f32_e32 v92, v71, v92
	v_add_f32_e32 v92, v72, v92
	v_add_f32_e32 v92, v73, v92
	v_cvt_pk_bf16_f32 v150, v68, v69
	v_cvt_pk_bf16_f32 v151, v70, v71
	s_waitcnt lgkmcnt(0)
	v_mfma_f32_32x32x16_bf16 v[96:111], v[136:139], v[64:67], v[96:111]
	ds_read_b64_tr_b16 v[136:137], v168 offset:60416
	ds_read_b64_tr_b16 v[138:139], v168 offset:60928
	ds_read_b128 v[64:67], v188 offset:3072
	v_add_f32_e32 v68, v74, v92
	v_add_f32_e32 v68, v75, v68
	v_add_f32_e32 v68, v76, v68
	v_add_f32_e32 v68, v77, v68
	v_cvt_pk_bf16_f32 v144, v72, v73
	v_cvt_pk_bf16_f32 v145, v74, v75
	s_waitcnt lgkmcnt(0)
	v_mfma_f32_32x32x16_bf16 v[112:127], v[132:135], v[64:67], v[112:127]
	ds_read_b64_tr_b16 v[72:73], v168 offset:64512
	ds_read_b64_tr_b16 v[74:75], v168 offset:65024
	ds_read_b128 v[64:67], v188 offset:3072
	v_add_f32_e32 v68, v78, v68
	v_add_f32_e32 v68, v79, v68
	v_add_f32_e32 v68, 0, v68
	v_cvt_pk_bf16_f32 v146, v76, v77
	v_cvt_pk_bf16_f32 v147, v78, v79
	s_waitcnt lgkmcnt(0)
; #define WAIT_BAR(N) asm volatile("s_waitcnt vmcnt(" #N ") lgkmcnt(0)\n\ts_barrier":::"memory")
;   #define RESC() do{ if(!NOMAX&&resc){ asm volatile("s_waitcnt lgkmcnt(0)":::"memory"); \
;       _Pragma("unroll") for(int d_=0;d_<2*VM;++d_) _Pragma("unroll") for(int r=0;r<16;++r)o[d_][r]*=wsf[crow(r,hi)]; } }while(0)
;   #define ROT() do{sl_prev=sl_cur;sl_cur=sl_next;sl_next=(sl_next==(NSLOT-1)*SLOTB)?0:sl_next+SLOTB;}while(0)
;   #define ENDW(tt) do{ if((tt)+3<NT){ if constexpr(VM==2){WAIT_BAR(3);}else{WAIT_BAR(2);} } else if((tt)+2<NT){ if constexpr(VM==2){WAIT_BAR(2);}else{WAIT_BAR(1);} } else {WAIT_BAR(0);} }while(0)
; template<int THRL,int VM,bool NOMAX> __device__ __forceinline__ void attn_unit(const bf16*Qb,const bf16*__restrict__ Kh,const bf16*__restrict__ Vh,bf16*Ob,const int NT,const int sp,float*wscr,char*shm){
;     ...
;   int t=1;
;   for(;t+5<NT;t+=2){
;     STEP(pB0,pB1,pA0,pA1,t,true,true,true);     if constexpr(VM==2){WAIT_BAR(3);}else{WAIT_BAR(2);} RESC(); ROT();
;     STEP(pA0,pA1,pB0,pB1,t+1,true,true,true);   if constexpr(VM==2){WAIT_BAR(3);}else{WAIT_BAR(2);} RESC(); ROT();
;   }
;     ...
;   for(;t+1<NT;t+=2){
;     STEP(pB0,pB1,pA0,pA1,t,(t+3<NT),(t+1<NT),(t+1<NT));       ENDW(t);   RESC(); ROT();
;     STEP(pA0,pA1,pB0,pB1,t+1,(t+4<NT),(t+2<NT),(t+2<NT));     ENDW(t+1); RESC(); ROT();
	v_mfma_f32_32x32x16_bf16 v[96:111], v[128:131], v[64:67], v[96:111]
	v_lshl_add_u64 v[64:65], v[174:175], 0, s[58:59]
	s_mov_b32 s86, m0
	s_mov_b32 m0, s35
	s_nop 0
	global_load_lds_dwordx4 v[64:65], off
	s_mov_b32 m0, s86
	s_add_i32 s85, s85, s17
	v_lshl_add_u64 v[64:65], v[170:171], 0, s[60:61]
	s_add_i32 s17, s85, 0xa000
	s_mov_b32 s35, m0
	s_mov_b32 m0, s17
	s_nop 0
	global_load_lds_dwordx4 v[64:65], off
	s_mov_b32 m0, s35
	v_lshl_add_u64 v[64:65], v[172:173], 0, s[60:61]
	s_add_i32 s35, s17, 0x2000
	s_mov_b32 s86, m0
	s_mov_b32 m0, s35
	s_nop 0
	global_load_lds_dwordx4 v[64:65], off
	s_mov_b32 m0, s86
	v_add_f32_e32 v198, v193, v68
	v_mfma_f32_32x32x16_bf16 v[48:63], v[156:159], v[178:181], v[48:63]
	ds_read_b64_tr_b16 v[76:77], v177 offset:40960
	ds_read_b64_tr_b16 v[78:79], v177 offset:41472
	v_exp_f32_e32 v112, v112
	v_exp_f32_e32 v113, v113
	v_mfma_f32_32x32x16_bf16 v[32:47], v[156:159], v[80:83], v[32:47]
	ds_read_b64_tr_b16 v[128:129], v177 offset:45056
	ds_read_b64_tr_b16 v[130:131], v177 offset:45568
	v_exp_f32_e32 v114, v114
	v_exp_f32_e32 v115, v115
	ds_read_b128 v[68:71], v234 offset:8192
	ds_read_b128 v[64:67], v234 offset:12288
	v_mfma_f32_32x32x16_bf16 v[48:63], v[152:155], v[84:87], v[48:63]
	ds_read_b64_tr_b16 v[132:133], v177 offset:41984
	ds_read_b64_tr_b16 v[134:135], v177 offset:42496
	v_exp_f32_e32 v116, v116
	v_exp_f32_e32 v117, v117
	ds_read_b128 v[164:167], v235 offset:8192
	ds_read_b128 v[92:95], v235 offset:12288
	v_mfma_f32_32x32x16_bf16 v[32:47], v[152:155], v[88:91], v[32:47]
	ds_read_b64_tr_b16 v[178:179], v177 offset:46080
	ds_read_b64_tr_b16 v[180:181], v177 offset:46592
	v_exp_f32_e32 v118, v118
	v_exp_f32_e32 v119, v119
	ds_read_b128 v[160:163], v236 offset:8192
	ds_read_b128 v[84:87], v236 offset:12288
	v_mfma_f32_32x32x16_bf16 v[48:63], v[148:151], v[194:197], v[48:63]
	ds_read_b64_tr_b16 v[190:191], v177 offset:43008
	ds_read_b64_tr_b16 v[192:193], v177 offset:43520
	v_exp_f32_e32 v120, v120
	v_exp_f32_e32 v121, v121
	ds_read_b128 v[88:91], v237 offset:8192
	ds_read_b128 v[80:83], v237 offset:12288
	v_mfma_f32_32x32x16_bf16 v[32:47], v[148:151], v[140:143], v[32:47]
	ds_read_b64_tr_b16 v[194:195], v177 offset:47104
	ds_read_b64_tr_b16 v[196:197], v177 offset:47616
	v_exp_f32_e32 v122, v122
	v_exp_f32_e32 v123, v123
	v_mfma_f32_32x32x16_bf16 v[48:63], v[144:147], v[136:139], v[48:63]
	ds_read_b64_tr_b16 v[140:141], v177 offset:44032
	ds_read_b64_tr_b16 v[142:143], v177 offset:44544
	v_exp_f32_e32 v124, v124
	v_exp_f32_e32 v125, v125
	v_mfma_f32_32x32x16_bf16 v[32:47], v[144:147], v[72:75], v[32:47]
	ds_read_b64_tr_b16 v[136:137], v177 offset:48128
	ds_read_b64_tr_b16 v[138:139], v177 offset:48640
	v_exp_f32_e32 v126, v126
	v_exp_f32_e32 v127, v127
	s_waitcnt lgkmcnt(14)
	v_mfma_f32_32x32x16_bf16 v[16:31], v[156:159], v[76:79], v[16:31]
	v_exp_f32_e32 v96, v96
	v_exp_f32_e32 v97, v97
	v_mfma_f32_32x32x16_bf16 v[0:15], v[156:159], v[128:131], v[0:15]
	v_exp_f32_e32 v98, v98
	v_exp_f32_e32 v99, v99
	v_mfma_f32_32x32x16_bf16 v[16:31], v[152:155], v[132:135], v[16:31]
	v_exp_f32_e32 v100, v100
	v_exp_f32_e32 v101, v101
	s_waitcnt lgkmcnt(12)
	v_mfma_f32_32x32x16_bf16 v[0:15], v[152:155], v[178:181], v[0:15]
	v_exp_f32_e32 v102, v102
	v_exp_f32_e32 v103, v103
	s_waitcnt lgkmcnt(8)
	v_mfma_f32_32x32x16_bf16 v[16:31], v[148:151], v[190:193], v[16:31]
	v_exp_f32_e32 v104, v104
	v_exp_f32_e32 v105, v105
	s_waitcnt lgkmcnt(4)
	v_mfma_f32_32x32x16_bf16 v[0:15], v[148:151], v[194:197], v[0:15]
	v_exp_f32_e32 v106, v106
	v_exp_f32_e32 v107, v107
	s_waitcnt lgkmcnt(2)
	v_mfma_f32_32x32x16_bf16 v[16:31], v[144:147], v[140:143], v[16:31]
	v_exp_f32_e32 v108, v108
	v_exp_f32_e32 v109, v109
	s_waitcnt lgkmcnt(0)
	v_mfma_f32_32x32x16_bf16 v[0:15], v[144:147], v[136:139], v[0:15]
	v_exp_f32_e32 v110, v110
	v_exp_f32_e32 v111, v111
	s_waitcnt vmcnt(3) lgkmcnt(0)
	s_barrier
	ds_read_b64_tr_b16 v[178:179], v168 offset:24576
	ds_read_b64_tr_b16 v[180:181], v168 offset:25088
	v_add_f32_e32 v76, v112, v113
	ds_read_b128 v[72:75], v188
	v_add_f32_e32 v76, v114, v76
	v_add_f32_e32 v76, v115, v76
	v_add_f32_e32 v76, v116, v76
	v_add_f32_e32 v76, v117, v76
	v_cvt_pk_bf16_f32 v156, v112, v113
	v_cvt_pk_bf16_f32 v157, v114, v115
	s_waitcnt lgkmcnt(0)
	v_mfma_f32_32x32x16_bf16 v[128:143], v[68:71], v[72:75], 0
	ds_read_b64_tr_b16 v[112:113], v168 offset:28672
	ds_read_b64_tr_b16 v[114:115], v168 offset:29184
	ds_read_b128 v[68:71], v188
	v_add_f32_e32 v72, v118, v76
	v_add_f32_e32 v72, v119, v72
	v_add_f32_e32 v72, v120, v72
	v_add_f32_e32 v144, v121, v72
	s_waitcnt lgkmcnt(0)
	v_mfma_f32_32x32x16_bf16 v[64:79], v[64:67], v[68:71], 0
	v_cvt_pk_bf16_f32 v158, v116, v117
	v_cvt_pk_bf16_f32 v159, v118, v119
	ds_read_b64_tr_b16 v[116:117], v168 offset:25600
	ds_read_b64_tr_b16 v[118:119], v168 offset:26112
	ds_read_b128 v[190:193], v188 offset:1024
	v_add_f32_e32 v144, v122, v144
	v_add_f32_e32 v144, v123, v144
	v_add_f32_e32 v144, v124, v144
	v_add_f32_e32 v144, v125, v144
	v_cvt_pk_bf16_f32 v152, v120, v121
	v_cvt_pk_bf16_f32 v153, v122, v123
	s_waitcnt lgkmcnt(0)
	v_mfma_f32_32x32x16_bf16 v[128:143], v[164:167], v[190:193], v[128:143]
	ds_read_b64_tr_b16 v[120:121], v168 offset:29696
	ds_read_b64_tr_b16 v[122:123], v168 offset:30208
	ds_read_b128 v[164:167], v188 offset:1024
	v_add_f32_e32 v144, v126, v144
	v_add_f32_e32 v144, v127, v144
	v_add_f32_e32 v144, v96, v144
	v_add_f32_e32 v144, v97, v144
	s_waitcnt lgkmcnt(0)
; #define WAIT_BAR(N) asm volatile("s_waitcnt vmcnt(" #N ") lgkmcnt(0)\n\ts_barrier":::"memory")
;   #define RESC() do{ if(!NOMAX&&resc){ asm volatile("s_waitcnt lgkmcnt(0)":::"memory"); \
;       _Pragma("unroll") for(int d_=0;d_<2*VM;++d_) _Pragma("unroll") for(int r=0;r<16;++r)o[d_][r]*=wsf[crow(r,hi)]; } }while(0)
;   #define ROT() do{sl_prev=sl_cur;sl_cur=sl_next;sl_next=(sl_next==(NSLOT-1)*SLOTB)?0:sl_next+SLOTB;}while(0)
;   #define ENDW(tt) do{ if((tt)+3<NT){ if constexpr(VM==2){WAIT_BAR(3);}else{WAIT_BAR(2);} } else if((tt)+2<NT){ if constexpr(VM==2){WAIT_BAR(2);}else{WAIT_BAR(1);} } else {WAIT_BAR(0);} }while(0)
; template<int THRL,int VM,bool NOMAX> __device__ __forceinline__ void attn_unit(const bf16*Qb,const bf16*__restrict__ Kh,const bf16*__restrict__ Vh,bf16*Ob,const int NT,const int sp,float*wscr,char*shm){
;     ...
;   int t=1;
;   for(;t+5<NT;t+=2){
;     STEP(pB0,pB1,pA0,pA1,t,true,true,true);     if constexpr(VM==2){WAIT_BAR(3);}else{WAIT_BAR(2);} RESC(); ROT();
;     STEP(pA0,pA1,pB0,pB1,t+1,true,true,true);   if constexpr(VM==2){WAIT_BAR(3);}else{WAIT_BAR(2);} RESC(); ROT();
;   }
;     ...
;   for(;t+1<NT;t+=2){
;     STEP(pB0,pB1,pA0,pA1,t,(t+3<NT),(t+1<NT),(t+1<NT));       ENDW(t);   RESC(); ROT();
;     STEP(pA0,pA1,pB0,pB1,t+1,(t+4<NT),(t+2<NT),(t+2<NT));     ENDW(t+1); RESC(); ROT();
	v_mfma_f32_32x32x16_bf16 v[64:79], v[92:95], v[164:167], v[64:79]
	v_cvt_pk_bf16_f32 v154, v124, v125
	v_cvt_pk_bf16_f32 v155, v126, v127
	ds_read_b64_tr_b16 v[92:93], v168 offset:26624
	ds_read_b64_tr_b16 v[94:95], v168 offset:27136
	ds_read_b128 v[124:127], v188 offset:2048
	v_add_f32_e32 v144, v98, v144
	v_add_f32_e32 v144, v99, v144
	v_add_f32_e32 v144, v100, v144
	v_add_f32_e32 v144, v101, v144
	v_cvt_pk_bf16_f32 v148, v96, v97
	v_cvt_pk_bf16_f32 v149, v98, v99
	s_waitcnt lgkmcnt(0)
	v_mfma_f32_32x32x16_bf16 v[128:143], v[160:163], v[124:127], v[128:143]
	ds_read_b64_tr_b16 v[96:97], v168 offset:30720
	ds_read_b64_tr_b16 v[98:99], v168 offset:31232
	ds_read_b128 v[124:127], v188 offset:2048
	v_add_f32_e32 v144, v102, v144
	v_add_f32_e32 v144, v103, v144
	v_add_f32_e32 v144, v104, v144
	v_add_f32_e32 v144, v105, v144
	s_waitcnt lgkmcnt(0)
	v_mfma_f32_32x32x16_bf16 v[64:79], v[84:87], v[124:127], v[64:79]
	v_cvt_pk_bf16_f32 v150, v100, v101
	v_cvt_pk_bf16_f32 v151, v102, v103
	ds_read_b64_tr_b16 v[100:101], v168 offset:27648
	ds_read_b64_tr_b16 v[102:103], v168 offset:28160
	ds_read_b128 v[84:87], v188 offset:3072
	v_add_f32_e32 v124, v106, v144
	v_add_f32_e32 v124, v107, v124
	v_add_f32_e32 v124, v108, v124
	v_add_f32_e32 v124, v109, v124
	v_cvt_pk_bf16_f32 v144, v104, v105
	v_cvt_pk_bf16_f32 v145, v106, v107
	s_waitcnt lgkmcnt(0)
	v_mfma_f32_32x32x16_bf16 v[128:143], v[88:91], v[84:87], v[128:143]
	ds_read_b64_tr_b16 v[88:89], v168 offset:31744
	ds_read_b64_tr_b16 v[90:91], v168 offset:32256
	ds_read_b128 v[84:87], v188 offset:3072
	v_add_f32_e32 v104, v110, v124
	v_add_f32_e32 v104, v111, v104
	v_add_f32_e32 v104, 0, v104
	v_cvt_pk_bf16_f32 v146, v108, v109
	s_waitcnt lgkmcnt(0)
	v_mfma_f32_32x32x16_bf16 v[64:79], v[80:83], v[84:87], v[64:79]
	v_cvt_pk_bf16_f32 v147, v110, v111
	v_lshl_add_u64 v[80:81], v[174:175], 0, s[62:63]
	s_add_i32 s86, s85, 0x2000
	s_mov_b32 s87, m0
	s_mov_b32 m0, s86
	s_nop 0
	global_load_lds_dwordx4 v[80:81], off
	s_mov_b32 m0, s87
	v_lshl_add_u64 v[80:81], v[170:171], 0, s[64:65]
	s_add_i32 s86, s85, 0xe000
	s_mov_b32 s87, m0
	s_mov_b32 m0, s86
	s_nop 0
	global_load_lds_dwordx4 v[80:81], off
	s_mov_b32 m0, s87
	v_lshl_add_u64 v[80:81], v[172:173], 0, s[64:65]
	s_add_i32 s85, s85, 0x10000
	s_mov_b32 s86, m0
	s_mov_b32 m0, s85
	s_nop 0
	global_load_lds_dwordx4 v[80:81], off
	s_mov_b32 m0, s86
	v_add_f32_e32 v198, v198, v104
	v_mfma_f32_32x32x16_bf16 v[48:63], v[156:159], v[178:181], v[48:63]
	ds_read_b64_tr_b16 v[104:105], v168 offset:32768
	ds_read_b64_tr_b16 v[106:107], v168 offset:33280
	v_exp_f32_e32 v128, v128
	v_exp_f32_e32 v129, v129
	v_mfma_f32_32x32x16_bf16 v[32:47], v[156:159], v[112:115], v[32:47]
	ds_read_b64_tr_b16 v[108:109], v168 offset:36864
	ds_read_b64_tr_b16 v[110:111], v168 offset:37376
	v_exp_f32_e32 v130, v130
	v_exp_f32_e32 v131, v131
	ds_read_b128 v[84:87], v234 offset:16384
	ds_read_b128 v[80:83], v234 offset:20480
	v_mfma_f32_32x32x16_bf16 v[48:63], v[152:155], v[116:119], v[48:63]
	ds_read_b64_tr_b16 v[178:179], v168 offset:33792
	ds_read_b64_tr_b16 v[180:181], v168 offset:34304
	v_exp_f32_e32 v132, v132
	v_exp_f32_e32 v133, v133
	ds_read_b128 v[164:167], v235 offset:16384
	ds_read_b128 v[124:127], v235 offset:20480
	v_mfma_f32_32x32x16_bf16 v[32:47], v[152:155], v[120:123], v[32:47]
	ds_read_b64_tr_b16 v[190:191], v168 offset:37888
	ds_read_b64_tr_b16 v[192:193], v168 offset:38400
	v_exp_f32_e32 v134, v134
	v_exp_f32_e32 v135, v135
	ds_read_b128 v[160:163], v236 offset:16384
	ds_read_b128 v[116:119], v236 offset:20480
	v_mfma_f32_32x32x16_bf16 v[48:63], v[148:151], v[92:95], v[48:63]
	ds_read_b64_tr_b16 v[194:195], v168 offset:34816
	ds_read_b64_tr_b16 v[196:197], v168 offset:35328
	v_exp_f32_e32 v136, v136
	v_exp_f32_e32 v137, v137
	ds_read_b128 v[120:123], v237 offset:16384
	ds_read_b128 v[112:115], v237 offset:20480
	v_mfma_f32_32x32x16_bf16 v[32:47], v[148:151], v[96:99], v[32:47]
	ds_read_b64_tr_b16 v[92:93], v168 offset:38912
	ds_read_b64_tr_b16 v[94:95], v168 offset:39424
	v_exp_f32_e32 v138, v138
	v_exp_f32_e32 v139, v139
	v_mfma_f32_32x32x16_bf16 v[48:63], v[144:147], v[100:103], v[48:63]
	ds_read_b64_tr_b16 v[96:97], v168 offset:35840
	ds_read_b64_tr_b16 v[98:99], v168 offset:36352
	v_exp_f32_e32 v140, v140
	v_exp_f32_e32 v141, v141
	v_mfma_f32_32x32x16_bf16 v[32:47], v[144:147], v[88:91], v[32:47]
	ds_read_b64_tr_b16 v[100:101], v168 offset:39936
	ds_read_b64_tr_b16 v[102:103], v168 offset:40448
	v_exp_f32_e32 v142, v142
	v_exp_f32_e32 v143, v143
	s_waitcnt lgkmcnt(14)
	v_mfma_f32_32x32x16_bf16 v[16:31], v[156:159], v[104:107], v[16:31]
	v_exp_f32_e32 v64, v64
	v_exp_f32_e32 v65, v65
	v_mfma_f32_32x32x16_bf16 v[0:15], v[156:159], v[108:111], v[0:15]
	v_exp_f32_e32 v66, v66
	v_exp_f32_e32 v67, v67
	v_mfma_f32_32x32x16_bf16 v[16:31], v[152:155], v[178:181], v[16:31]
	v_exp_f32_e32 v68, v68
	v_exp_f32_e32 v69, v69
	s_waitcnt lgkmcnt(12)
	v_mfma_f32_32x32x16_bf16 v[0:15], v[152:155], v[190:193], v[0:15]
	v_exp_f32_e32 v70, v70
	v_exp_f32_e32 v71, v71
	s_waitcnt lgkmcnt(8)
	v_mfma_f32_32x32x16_bf16 v[16:31], v[148:151], v[194:197], v[16:31]
	v_exp_f32_e32 v72, v72
	v_exp_f32_e32 v73, v73
	s_waitcnt lgkmcnt(4)
	v_mfma_f32_32x32x16_bf16 v[0:15], v[148:151], v[92:95], v[0:15]
	v_exp_f32_e32 v74, v74
	v_exp_f32_e32 v75, v75
	s_waitcnt lgkmcnt(2)
	v_mfma_f32_32x32x16_bf16 v[16:31], v[144:147], v[96:99], v[16:31]
	v_exp_f32_e32 v76, v76
	v_exp_f32_e32 v77, v77
	s_waitcnt lgkmcnt(0)
	v_mfma_f32_32x32x16_bf16 v[0:15], v[144:147], v[100:103], v[0:15]
	v_exp_f32_e32 v78, v78
	v_exp_f32_e32 v79, v79
	s_waitcnt vmcnt(3) lgkmcnt(0)
	s_barrier
; #define WAIT_BAR(N) asm volatile("s_waitcnt vmcnt(" #N ") lgkmcnt(0)\n\ts_barrier":::"memory")
;   #define RESC() do{ if(!NOMAX&&resc){ asm volatile("s_waitcnt lgkmcnt(0)":::"memory"); \
;       _Pragma("unroll") for(int d_=0;d_<2*VM;++d_) _Pragma("unroll") for(int r=0;r<16;++r)o[d_][r]*=wsf[crow(r,hi)]; } }while(0)
;   #define ROT() do{sl_prev=sl_cur;sl_cur=sl_next;sl_next=(sl_next==(NSLOT-1)*SLOTB)?0:sl_next+SLOTB;}while(0)
;   #define ENDW(tt) do{ if((tt)+3<NT){ if constexpr(VM==2){WAIT_BAR(3);}else{WAIT_BAR(2);} } else if((tt)+2<NT){ if constexpr(VM==2){WAIT_BAR(2);}else{WAIT_BAR(1);} } else {WAIT_BAR(0);} }while(0)
; template<int THRL,int VM,bool NOMAX> __device__ __forceinline__ void attn_unit(const bf16*Qb,const bf16*__restrict__ Kh,const bf16*__restrict__ Vh,bf16*Ob,const int NT,const int sp,float*wscr,char*shm){
;     ...
;   int t=1;
;   for(;t+5<NT;t+=2){
;     STEP(pB0,pB1,pA0,pA1,t,true,true,true);     if constexpr(VM==2){WAIT_BAR(3);}else{WAIT_BAR(2);} RESC(); ROT();
;     STEP(pA0,pA1,pB0,pB1,t+1,true,true,true);   if constexpr(VM==2){WAIT_BAR(3);}else{WAIT_BAR(2);} RESC(); ROT();
;   }
;     ...
;   for(;t+1<NT;t+=2){
;     STEP(pB0,pB1,pA0,pA1,t,(t+3<NT),(t+1<NT),(t+1<NT));       ENDW(t);   RESC(); ROT();
;     STEP(pA0,pA1,pB0,pB1,t+1,(t+4<NT),(t+2<NT),(t+2<NT));     ENDW(t+1); RESC(); ROT();
	ds_read_b64_tr_b16 v[178:179], v168 offset:40960
	ds_read_b64_tr_b16 v[180:181], v168 offset:41472
	v_add_f32_e32 v92, v128, v129
	ds_read_b128 v[88:91], v188
	v_add_f32_e32 v92, v130, v92
	v_add_f32_e32 v92, v131, v92
	v_add_f32_e32 v92, v132, v92
	v_add_f32_e32 v92, v133, v92
	v_cvt_pk_bf16_f32 v156, v128, v129
	v_cvt_pk_bf16_f32 v157, v130, v131
	s_waitcnt lgkmcnt(0)
	v_mfma_f32_32x32x16_bf16 v[96:111], v[84:87], v[88:91], 0
	ds_read_b64_tr_b16 v[128:129], v168 offset:45056
	ds_read_b64_tr_b16 v[130:131], v168 offset:45568
	ds_read_b128 v[84:87], v188
	v_add_f32_e32 v88, v134, v92
	v_add_f32_e32 v88, v135, v88
	v_add_f32_e32 v88, v136, v88
	v_add_f32_e32 v144, v137, v88
	v_cvt_pk_bf16_f32 v158, v132, v133
	v_cvt_pk_bf16_f32 v159, v134, v135
	s_waitcnt lgkmcnt(0)
	v_mfma_f32_32x32x16_bf16 v[80:95], v[80:83], v[84:87], 0
	ds_read_b64_tr_b16 v[132:133], v168 offset:41984
	ds_read_b64_tr_b16 v[134:135], v168 offset:42496
	ds_read_b128 v[190:193], v188 offset:1024
	v_add_f32_e32 v144, v138, v144
	v_add_f32_e32 v144, v139, v144
	v_add_f32_e32 v144, v140, v144
	v_add_f32_e32 v144, v141, v144
	v_cvt_pk_bf16_f32 v152, v136, v137
	v_cvt_pk_bf16_f32 v153, v138, v139
	s_waitcnt lgkmcnt(0)
	v_mfma_f32_32x32x16_bf16 v[96:111], v[164:167], v[190:193], v[96:111]
	ds_read_b64_tr_b16 v[136:137], v168 offset:46080
	ds_read_b64_tr_b16 v[138:139], v168 offset:46592
	ds_read_b128 v[164:167], v188 offset:1024
	v_add_f32_e32 v144, v142, v144
	v_add_f32_e32 v144, v143, v144
	v_add_f32_e32 v144, v64, v144
	v_add_f32_e32 v144, v65, v144
	v_cvt_pk_bf16_f32 v154, v140, v141
	v_cvt_pk_bf16_f32 v155, v142, v143
	s_waitcnt lgkmcnt(0)
	v_mfma_f32_32x32x16_bf16 v[80:95], v[124:127], v[164:167], v[80:95]
	ds_read_b64_tr_b16 v[124:125], v168 offset:43008
	ds_read_b64_tr_b16 v[126:127], v168 offset:43520
	ds_read_b128 v[140:143], v188 offset:2048
	v_add_f32_e32 v144, v66, v144
	v_add_f32_e32 v144, v67, v144
	v_add_f32_e32 v144, v68, v144
	v_add_f32_e32 v144, v69, v144
	v_cvt_pk_bf16_f32 v148, v64, v65
	v_cvt_pk_bf16_f32 v149, v66, v67
	s_waitcnt lgkmcnt(0)
	v_mfma_f32_32x32x16_bf16 v[96:111], v[160:163], v[140:143], v[96:111]
	ds_read_b64_tr_b16 v[190:191], v168 offset:47104
	ds_read_b64_tr_b16 v[192:193], v168 offset:47616
	ds_read_b128 v[64:67], v188 offset:2048
	v_add_f32_e32 v140, v70, v144
	v_add_f32_e32 v140, v71, v140
	v_add_f32_e32 v140, v72, v140
	v_add_f32_e32 v140, v73, v140
	v_cvt_pk_bf16_f32 v150, v68, v69
	v_cvt_pk_bf16_f32 v151, v70, v71
	s_waitcnt lgkmcnt(0)
	v_mfma_f32_32x32x16_bf16 v[80:95], v[116:119], v[64:67], v[80:95]
	ds_read_b64_tr_b16 v[116:117], v168 offset:44032
	ds_read_b64_tr_b16 v[118:119], v168 offset:44544
	ds_read_b128 v[64:67], v188 offset:3072
	v_add_f32_e32 v68, v74, v140
	v_add_f32_e32 v68, v75, v68
	v_add_f32_e32 v68, v76, v68
	v_add_f32_e32 v68, v77, v68
	v_cvt_pk_bf16_f32 v144, v72, v73
	v_cvt_pk_bf16_f32 v145, v74, v75
	s_waitcnt lgkmcnt(0)
	v_mfma_f32_32x32x16_bf16 v[96:111], v[120:123], v[64:67], v[96:111]
	ds_read_b64_tr_b16 v[72:73], v168 offset:48128
	ds_read_b64_tr_b16 v[74:75], v168 offset:48640
	ds_read_b128 v[64:67], v188 offset:3072
	v_add_f32_e32 v68, v78, v68
	v_add_f32_e32 v68, v79, v68
	v_add_f32_e32 v68, 0, v68
	v_cvt_pk_bf16_f32 v146, v76, v77
	v_cvt_pk_bf16_f32 v147, v78, v79
	s_waitcnt lgkmcnt(0)
	v_mfma_f32_32x32x16_bf16 v[80:95], v[112:115], v[64:67], v[80:95]
	v_lshl_add_u64 v[64:65], v[170:171], 0, s[58:59]
	s_mov_b32 s85, m0
	s_mov_b32 m0, s16
	s_nop 0
	global_load_lds_dwordx4 v[64:65], off
	s_mov_b32 m0, s85
	v_lshl_add_u64 v[64:65], v[172:173], 0, s[58:59]
	s_addk_i32 s16, 0x2000
	s_mov_b32 s85, m0
	s_mov_b32 m0, s16
	s_nop 0
	global_load_lds_dwordx4 v[64:65], off
	s_mov_b32 m0, s85
	v_add_f32_e32 v174, v198, v68
	v_mfma_f32_32x32x16_bf16 v[48:63], v[156:159], v[178:181], v[48:63]
	ds_read_b64_tr_b16 v[76:77], v168 offset:49152
	ds_read_b64_tr_b16 v[78:79], v168 offset:49664
	v_exp_f32_e32 v96, v96
	v_exp_f32_e32 v97, v97
	v_mfma_f32_32x32x16_bf16 v[32:47], v[156:159], v[128:131], v[32:47]
	ds_read_b64_tr_b16 v[112:113], v168 offset:53248
	ds_read_b64_tr_b16 v[114:115], v168 offset:53760
	v_exp_f32_e32 v98, v98
	v_exp_f32_e32 v99, v99
	ds_read_b128 v[68:71], v234
	ds_read_b128 v[64:67], v234 offset:4096
	v_mfma_f32_32x32x16_bf16 v[48:63], v[152:155], v[132:135], v[48:63]
	ds_read_b64_tr_b16 v[120:121], v168 offset:50176
	ds_read_b64_tr_b16 v[122:123], v168 offset:50688
	v_exp_f32_e32 v100, v100
	v_exp_f32_e32 v101, v101
	ds_read_b128 v[164:167], v235
	ds_read_b128 v[140:143], v235 offset:4096
	v_mfma_f32_32x32x16_bf16 v[32:47], v[152:155], v[136:139], v[32:47]
	ds_read_b64_tr_b16 v[178:179], v168 offset:54272
	ds_read_b64_tr_b16 v[180:181], v168 offset:54784
	v_exp_f32_e32 v102, v102
	v_exp_f32_e32 v103, v103
	ds_read_b128 v[160:163], v236
	ds_read_b128 v[132:135], v236 offset:4096
	v_mfma_f32_32x32x16_bf16 v[48:63], v[148:151], v[124:127], v[48:63]
	ds_read_b64_tr_b16 v[194:195], v168 offset:51200
	ds_read_b64_tr_b16 v[196:197], v168 offset:51712
	v_exp_f32_e32 v104, v104
	v_exp_f32_e32 v105, v105
	ds_read_b128 v[136:139], v237
	ds_read_b128 v[128:131], v237 offset:4096
	v_mfma_f32_32x32x16_bf16 v[32:47], v[148:151], v[190:193], v[32:47]
	ds_read_b64_tr_b16 v[124:125], v168 offset:55296
	ds_read_b64_tr_b16 v[126:127], v168 offset:55808
	v_exp_f32_e32 v106, v106
	v_exp_f32_e32 v107, v107
	v_mfma_f32_32x32x16_bf16 v[48:63], v[144:147], v[116:119], v[48:63]
	ds_read_b64_tr_b16 v[190:191], v168 offset:52224
	ds_read_b64_tr_b16 v[192:193], v168 offset:52736
	v_exp_f32_e32 v108, v108
	v_exp_f32_e32 v109, v109
	v_mfma_f32_32x32x16_bf16 v[32:47], v[144:147], v[72:75], v[32:47]
	ds_read_b64_tr_b16 v[116:117], v168 offset:56320
	ds_read_b64_tr_b16 v[118:119], v168 offset:56832
	v_exp_f32_e32 v110, v110
	v_exp_f32_e32 v111, v111
	s_waitcnt lgkmcnt(14)
	v_mfma_f32_32x32x16_bf16 v[16:31], v[156:159], v[76:79], v[16:31]
	v_exp_f32_e32 v80, v80
	v_exp_f32_e32 v81, v81
	v_mfma_f32_32x32x16_bf16 v[0:15], v[156:159], v[112:115], v[0:15]
	v_exp_f32_e32 v82, v82
	v_exp_f32_e32 v83, v83
	v_mfma_f32_32x32x16_bf16 v[16:31], v[152:155], v[120:123], v[16:31]
	v_exp_f32_e32 v84, v84
	v_exp_f32_e32 v85, v85
	s_waitcnt lgkmcnt(12)
	v_mfma_f32_32x32x16_bf16 v[0:15], v[152:155], v[178:181], v[0:15]
	v_exp_f32_e32 v86, v86
	v_exp_f32_e32 v87, v87
	s_waitcnt lgkmcnt(8)
	v_mfma_f32_32x32x16_bf16 v[16:31], v[148:151], v[194:197], v[16:31]
	v_exp_f32_e32 v88, v88
	v_exp_f32_e32 v89, v89
	s_waitcnt lgkmcnt(4)
	v_mfma_f32_32x32x16_bf16 v[0:15], v[148:151], v[124:127], v[0:15]
	v_exp_f32_e32 v90, v90
	v_exp_f32_e32 v91, v91
	s_waitcnt lgkmcnt(2)
	v_mfma_f32_32x32x16_bf16 v[16:31], v[144:147], v[190:193], v[16:31]
	v_exp_f32_e32 v92, v92
	v_exp_f32_e32 v93, v93
	s_waitcnt lgkmcnt(0)
	v_mfma_f32_32x32x16_bf16 v[0:15], v[144:147], v[116:119], v[0:15]
	v_exp_f32_e32 v94, v94
	v_exp_f32_e32 v95, v95
	s_waitcnt vmcnt(2) lgkmcnt(0)
	s_barrier
; #define WAIT_BAR(N) asm volatile("s_waitcnt vmcnt(" #N ") lgkmcnt(0)\n\ts_barrier":::"memory")
;   #define RESC() do{ if(!NOMAX&&resc){ asm volatile("s_waitcnt lgkmcnt(0)":::"memory"); \
;       _Pragma("unroll") for(int d_=0;d_<2*VM;++d_) _Pragma("unroll") for(int r=0;r<16;++r)o[d_][r]*=wsf[crow(r,hi)]; } }while(0)
;   #define ROT() do{sl_prev=sl_cur;sl_cur=sl_next;sl_next=(sl_next==(NSLOT-1)*SLOTB)?0:sl_next+SLOTB;}while(0)
;   #define ENDW(tt) do{ if((tt)+3<NT){ if constexpr(VM==2){WAIT_BAR(3);}else{WAIT_BAR(2);} } else if((tt)+2<NT){ if constexpr(VM==2){WAIT_BAR(2);}else{WAIT_BAR(1);} } else {WAIT_BAR(0);} }while(0)
; template<int THRL,int VM,bool NOMAX> __device__ __forceinline__ void attn_unit(const bf16*Qb,const bf16*__restrict__ Kh,const bf16*__restrict__ Vh,bf16*Ob,const int NT,const int sp,float*wscr,char*shm){
;     ...
;   int t=1;
;   for(;t+5<NT;t+=2){
;     STEP(pB0,pB1,pA0,pA1,t,true,true,true);     if constexpr(VM==2){WAIT_BAR(3);}else{WAIT_BAR(2);} RESC(); ROT();
;     STEP(pA0,pA1,pB0,pB1,t+1,true,true,true);   if constexpr(VM==2){WAIT_BAR(3);}else{WAIT_BAR(2);} RESC(); ROT();
;   }
;     ...
;   for(;t+1<NT;t+=2){
;     STEP(pB0,pB1,pA0,pA1,t,(t+3<NT),(t+1<NT),(t+1<NT));       ENDW(t);   RESC(); ROT();
;     STEP(pA0,pA1,pB0,pB1,t+1,(t+4<NT),(t+2<NT),(t+2<NT));     ENDW(t+1); RESC(); ROT();
	ds_read_b64_tr_b16 v[178:179], v168 offset:57344
	ds_read_b64_tr_b16 v[180:181], v168 offset:57856
	v_add_f32_e32 v76, v96, v97
	ds_read_b128 v[72:75], v188
	v_add_f32_e32 v76, v98, v76
	v_add_f32_e32 v76, v99, v76
	v_add_f32_e32 v76, v100, v76
	v_add_f32_e32 v76, v101, v76
	v_cvt_pk_bf16_f32 v156, v96, v97
	v_cvt_pk_bf16_f32 v157, v98, v99
	s_waitcnt lgkmcnt(0)
	v_mfma_f32_32x32x16_bf16 v[112:127], v[68:71], v[72:75], 0
	ds_read_b64_tr_b16 v[96:97], v168 offset:61440
	ds_read_b64_tr_b16 v[98:99], v168 offset:61952
	ds_read_b128 v[68:71], v188
	v_add_f32_e32 v72, v102, v76
	v_add_f32_e32 v72, v103, v72
	v_add_f32_e32 v72, v104, v72
	v_add_f32_e32 v144, v105, v72
	s_waitcnt lgkmcnt(0)
	v_mfma_f32_32x32x16_bf16 v[64:79], v[64:67], v[68:71], 0
	v_cvt_pk_bf16_f32 v158, v100, v101
	v_cvt_pk_bf16_f32 v159, v102, v103
	ds_read_b64_tr_b16 v[100:101], v168 offset:58368
	ds_read_b64_tr_b16 v[102:103], v168 offset:58880
	ds_read_b128 v[190:193], v188 offset:1024
	v_add_f32_e32 v144, v106, v144
	v_add_f32_e32 v144, v107, v144
	v_add_f32_e32 v144, v108, v144
	v_add_f32_e32 v144, v109, v144
	v_cvt_pk_bf16_f32 v152, v104, v105
	v_cvt_pk_bf16_f32 v153, v106, v107
	s_waitcnt lgkmcnt(0)
	v_mfma_f32_32x32x16_bf16 v[112:127], v[164:167], v[190:193], v[112:127]
	ds_read_b64_tr_b16 v[104:105], v168 offset:62464
	ds_read_b64_tr_b16 v[106:107], v168 offset:62976
	ds_read_b128 v[164:167], v188 offset:1024
	v_add_f32_e32 v144, v110, v144
	v_add_f32_e32 v144, v111, v144
	v_add_f32_e32 v144, v80, v144
	v_add_f32_e32 v144, v81, v144
	s_waitcnt lgkmcnt(0)
	v_mfma_f32_32x32x16_bf16 v[64:79], v[140:143], v[164:167], v[64:79]
	v_cvt_pk_bf16_f32 v154, v108, v109
	v_cvt_pk_bf16_f32 v155, v110, v111
	ds_read_b64_tr_b16 v[108:109], v168 offset:59392
	ds_read_b64_tr_b16 v[110:111], v168 offset:59904
	ds_read_b128 v[140:143], v188 offset:2048
	v_add_f32_e32 v144, v82, v144
	v_add_f32_e32 v144, v83, v144
	v_add_f32_e32 v144, v84, v144
	v_add_f32_e32 v144, v85, v144
	v_cvt_pk_bf16_f32 v148, v80, v81
	v_cvt_pk_bf16_f32 v149, v82, v83
	s_waitcnt lgkmcnt(0)
	v_mfma_f32_32x32x16_bf16 v[112:127], v[160:163], v[140:143], v[112:127]
	ds_read_b64_tr_b16 v[190:191], v168 offset:63488
	ds_read_b64_tr_b16 v[192:193], v168 offset:64000
	ds_read_b128 v[80:83], v188 offset:2048
	v_add_f32_e32 v140, v86, v144
	v_add_f32_e32 v140, v87, v140
	v_add_f32_e32 v140, v88, v140
	v_add_f32_e32 v140, v89, v140
	s_waitcnt lgkmcnt(0)
	v_mfma_f32_32x32x16_bf16 v[64:79], v[132:135], v[80:83], v[64:79]
	v_cvt_pk_bf16_f32 v150, v84, v85
	v_cvt_pk_bf16_f32 v151, v86, v87
	ds_read_b64_tr_b16 v[84:85], v168 offset:60416
	ds_read_b64_tr_b16 v[86:87], v168 offset:60928
	ds_read_b128 v[80:83], v188 offset:3072
	v_add_f32_e32 v132, v90, v140
	v_add_f32_e32 v132, v91, v132
	v_add_f32_e32 v132, v92, v132
	v_add_f32_e32 v132, v93, v132
	v_cvt_pk_bf16_f32 v144, v88, v89
	v_cvt_pk_bf16_f32 v145, v90, v91
	s_waitcnt lgkmcnt(0)
	v_mfma_f32_32x32x16_bf16 v[112:127], v[136:139], v[80:83], v[112:127]
	ds_read_b64_tr_b16 v[88:89], v168 offset:64512
	ds_read_b64_tr_b16 v[90:91], v168 offset:65024
	ds_read_b128 v[80:83], v188 offset:3072
	v_add_f32_e32 v132, v94, v132
	v_add_f32_e32 v132, v95, v132
	v_add_f32_e32 v132, 0, v132
	v_cvt_pk_bf16_f32 v146, v92, v93
	s_waitcnt lgkmcnt(0)
	v_mfma_f32_32x32x16_bf16 v[64:79], v[128:131], v[80:83], v[64:79]
	v_cvt_pk_bf16_f32 v147, v94, v95
	v_lshl_add_u64 v[80:81], v[170:171], 0, s[62:63]
	s_mov_b32 s16, m0
	s_mov_b32 m0, s17
	s_nop 0
	global_load_lds_dwordx4 v[80:81], off
	s_mov_b32 m0, s16
	v_lshl_add_u64 v[80:81], v[172:173], 0, s[62:63]
	s_mov_b32 s16, m0
	s_mov_b32 m0, s35
	s_nop 0
	global_load_lds_dwordx4 v[80:81], off
	s_mov_b32 m0, s16
	v_add_f32_e32 v174, v174, v132
	v_mfma_f32_32x32x16_bf16 v[48:63], v[156:159], v[178:181], v[48:63]
	ds_read_b64_tr_b16 v[92:93], v177 offset:40960
	ds_read_b64_tr_b16 v[94:95], v177 offset:41472
	v_exp_f32_e32 v112, v112
	v_exp_f32_e32 v113, v113
	v_mfma_f32_32x32x16_bf16 v[32:47], v[156:159], v[96:99], v[32:47]
	ds_read_b64_tr_b16 v[170:171], v177 offset:45056
	ds_read_b64_tr_b16 v[172:173], v177 offset:45568
	v_exp_f32_e32 v114, v114
	v_exp_f32_e32 v115, v115
	ds_read_b128 v[80:83], v234 offset:8192
	ds_read_b128 v[96:99], v234 offset:12288
	v_mfma_f32_32x32x16_bf16 v[48:63], v[152:155], v[100:103], v[48:63]
	ds_read_b64_tr_b16 v[178:179], v177 offset:41984
	ds_read_b64_tr_b16 v[180:181], v177 offset:42496
	v_exp_f32_e32 v116, v116
	v_exp_f32_e32 v117, v117
	ds_read_b128 v[164:167], v235 offset:8192
	ds_read_b128 v[140:143], v235 offset:12288
	v_mfma_f32_32x32x16_bf16 v[32:47], v[152:155], v[104:107], v[32:47]
	ds_read_b64_tr_b16 v[100:101], v177 offset:46080
	ds_read_b64_tr_b16 v[102:103], v177 offset:46592
	v_exp_f32_e32 v118, v118
	v_exp_f32_e32 v119, v119
	ds_read_b128 v[160:163], v236 offset:8192
	ds_read_b128 v[132:135], v236 offset:12288
	v_mfma_f32_32x32x16_bf16 v[48:63], v[148:151], v[108:111], v[48:63]
	ds_read_b64_tr_b16 v[104:105], v177 offset:43008
	ds_read_b64_tr_b16 v[106:107], v177 offset:43520
	v_exp_f32_e32 v120, v120
	v_exp_f32_e32 v121, v121
	ds_read_b128 v[136:139], v237 offset:8192
	ds_read_b128 v[128:131], v237 offset:12288
	v_mfma_f32_32x32x16_bf16 v[32:47], v[148:151], v[190:193], v[32:47]
	ds_read_b64_tr_b16 v[108:109], v177 offset:47104
	ds_read_b64_tr_b16 v[110:111], v177 offset:47616
	v_exp_f32_e32 v122, v122
	v_exp_f32_e32 v123, v123
	v_mfma_f32_32x32x16_bf16 v[48:63], v[144:147], v[84:87], v[48:63]
	ds_read_b64_tr_b16 v[190:191], v177 offset:44032
	ds_read_b64_tr_b16 v[192:193], v177 offset:44544
	v_exp_f32_e32 v124, v124
	v_exp_f32_e32 v125, v125
	v_mfma_f32_32x32x16_bf16 v[32:47], v[144:147], v[88:91], v[32:47]
	ds_read_b64_tr_b16 v[84:85], v177 offset:48128
	ds_read_b64_tr_b16 v[86:87], v177 offset:48640
	v_exp_f32_e32 v126, v126
	v_exp_f32_e32 v127, v127
	s_waitcnt lgkmcnt(14)
	v_mfma_f32_32x32x16_bf16 v[16:31], v[156:159], v[92:95], v[16:31]
	v_exp_f32_e32 v64, v64
	v_exp_f32_e32 v65, v65
	v_mfma_f32_32x32x16_bf16 v[0:15], v[156:159], v[170:173], v[0:15]
	v_exp_f32_e32 v66, v66
	v_exp_f32_e32 v67, v67
	v_mfma_f32_32x32x16_bf16 v[16:31], v[152:155], v[178:181], v[16:31]
	v_exp_f32_e32 v68, v68
	v_exp_f32_e32 v69, v69
	s_waitcnt lgkmcnt(12)
	v_mfma_f32_32x32x16_bf16 v[0:15], v[152:155], v[100:103], v[0:15]
	v_exp_f32_e32 v70, v70
	v_exp_f32_e32 v71, v71
	s_waitcnt lgkmcnt(8)
	v_mfma_f32_32x32x16_bf16 v[16:31], v[148:151], v[104:107], v[16:31]
	v_exp_f32_e32 v72, v72
	v_exp_f32_e32 v73, v73
	s_waitcnt lgkmcnt(4)
	v_mfma_f32_32x32x16_bf16 v[0:15], v[148:151], v[108:111], v[0:15]
	v_exp_f32_e32 v74, v74
	v_exp_f32_e32 v75, v75
	s_waitcnt lgkmcnt(2)
	v_mfma_f32_32x32x16_bf16 v[16:31], v[144:147], v[190:193], v[16:31]
	v_exp_f32_e32 v76, v76
	v_exp_f32_e32 v77, v77
	s_waitcnt lgkmcnt(0)
	v_mfma_f32_32x32x16_bf16 v[0:15], v[144:147], v[84:87], v[0:15]
	v_exp_f32_e32 v78, v78
	v_exp_f32_e32 v79, v79
	s_waitcnt vmcnt(0) lgkmcnt(0)
	s_barrier
	ds_read_b64_tr_b16 v[170:171], v168 offset:24576
	ds_read_b64_tr_b16 v[172:173], v168 offset:25088
	v_add_f32_e32 v88, v112, v113
	ds_read_b128 v[84:87], v188
	v_add_f32_e32 v88, v114, v88
	v_add_f32_e32 v88, v115, v88
	v_add_f32_e32 v88, v116, v88
	v_add_f32_e32 v104, v117, v88
	v_cvt_pk_bf16_f32 v156, v112, v113
	v_cvt_pk_bf16_f32 v157, v114, v115
	s_waitcnt lgkmcnt(0)
	v_mfma_f32_32x32x16_bf16 v[80:95], v[80:83], v[84:87], 0
	ds_read_b64_tr_b16 v[112:113], v168 offset:28672
	ds_read_b64_tr_b16 v[114:115], v168 offset:29184
	ds_read_b128 v[100:103], v188
	v_add_f32_e32 v104, v118, v104
	v_add_f32_e32 v104, v119, v104
	v_add_f32_e32 v104, v120, v104
	v_add_f32_e32 v144, v121, v104
	v_cvt_pk_bf16_f32 v158, v116, v117
	v_cvt_pk_bf16_f32 v159, v118, v119
	s_waitcnt lgkmcnt(0)
	v_mfma_f32_32x32x16_bf16 v[96:111], v[96:99], v[100:103], 0
	ds_read_b64_tr_b16 v[116:117], v168 offset:25600
	ds_read_b64_tr_b16 v[118:119], v168 offset:26112
	ds_read_b128 v[178:181], v188 offset:1024
	v_add_f32_e32 v144, v122, v144
	v_add_f32_e32 v144, v123, v144
	v_add_f32_e32 v144, v124, v144
	v_add_f32_e32 v144, v125, v144
	v_cvt_pk_bf16_f32 v152, v120, v121
	v_cvt_pk_bf16_f32 v153, v122, v123
	s_waitcnt lgkmcnt(0)
	v_mfma_f32_32x32x16_bf16 v[80:95], v[164:167], v[178:181], v[80:95]
	ds_read_b64_tr_b16 v[120:121], v168 offset:29696
	ds_read_b64_tr_b16 v[122:123], v168 offset:30208
	ds_read_b128 v[164:167], v188 offset:1024
	v_add_f32_e32 v144, v126, v144
	v_add_f32_e32 v144, v127, v144
	v_add_f32_e32 v144, v64, v144
	v_add_f32_e32 v144, v65, v144
	v_cvt_pk_bf16_f32 v154, v124, v125
	v_cvt_pk_bf16_f32 v155, v126, v127
	s_waitcnt lgkmcnt(0)
	v_mfma_f32_32x32x16_bf16 v[96:111], v[140:143], v[164:167], v[96:111]
	ds_read_b64_tr_b16 v[124:125], v168 offset:26624
	ds_read_b64_tr_b16 v[126:127], v168 offset:27136
	ds_read_b128 v[140:143], v188 offset:2048
	v_add_f32_e32 v144, v66, v144
	v_add_f32_e32 v144, v67, v144
	v_add_f32_e32 v144, v68, v144
	v_add_f32_e32 v144, v69, v144
	v_cvt_pk_bf16_f32 v148, v64, v65
	v_cvt_pk_bf16_f32 v149, v66, v67
	s_waitcnt lgkmcnt(0)
	v_mfma_f32_32x32x16_bf16 v[80:95], v[160:163], v[140:143], v[80:95]
	ds_read_b64_tr_b16 v[64:65], v168 offset:30720
	ds_read_b64_tr_b16 v[66:67], v168 offset:31232
	ds_read_b128 v[140:143], v188 offset:2048
	v_add_f32_e32 v144, v70, v144
	v_add_f32_e32 v144, v71, v144
	v_add_f32_e32 v144, v72, v144
	v_add_f32_e32 v144, v73, v144
	v_cvt_pk_bf16_f32 v150, v68, v69
	v_cvt_pk_bf16_f32 v151, v70, v71
	s_waitcnt lgkmcnt(0)
	v_mfma_f32_32x32x16_bf16 v[96:111], v[132:135], v[140:143], v[96:111]
	ds_read_b64_tr_b16 v[68:69], v168 offset:27648
	ds_read_b64_tr_b16 v[70:71], v168 offset:28160
	ds_read_b128 v[132:135], v188 offset:3072
	v_add_f32_e32 v140, v74, v144
	v_add_f32_e32 v140, v75, v140
	v_add_f32_e32 v140, v76, v140
	v_add_f32_e32 v140, v77, v140
	v_cvt_pk_bf16_f32 v144, v72, v73
	v_cvt_pk_bf16_f32 v145, v74, v75
	s_waitcnt lgkmcnt(0)
	v_mfma_f32_32x32x16_bf16 v[80:95], v[136:139], v[132:135], v[80:95]
	ds_read_b64_tr_b16 v[72:73], v168 offset:31744
	ds_read_b64_tr_b16 v[74:75], v168 offset:32256
	ds_read_b128 v[132:135], v188 offset:3072
	v_add_f32_e32 v136, v78, v140
	v_add_f32_e32 v136, v79, v136
	v_add_f32_e32 v136, 0, v136
	v_cvt_pk_bf16_f32 v146, v76, v77
	v_cvt_pk_bf16_f32 v147, v78, v79
	s_waitcnt lgkmcnt(0)
	v_mfma_f32_32x32x16_bf16 v[96:111], v[128:131], v[132:135], v[96:111]
	v_mfma_f32_32x32x16_bf16 v[48:63], v[156:159], v[170:173], v[48:63]
	ds_read_b64_tr_b16 v[76:77], v168 offset:32768
	ds_read_b64_tr_b16 v[78:79], v168 offset:33280
	v_exp_f32_e32 v80, v80
	v_exp_f32_e32 v81, v81
	v_mfma_f32_32x32x16_bf16 v[32:47], v[156:159], v[112:115], v[32:47]
	ds_read_b64_tr_b16 v[128:129], v168 offset:36864
	ds_read_b64_tr_b16 v[130:131], v168 offset:37376
	v_exp_f32_e32 v82, v82
	v_exp_f32_e32 v83, v83
	v_mfma_f32_32x32x16_bf16 v[48:63], v[152:155], v[116:119], v[48:63]
	ds_read_b64_tr_b16 v[112:113], v168 offset:33792
	ds_read_b64_tr_b16 v[114:115], v168 offset:34304
	v_exp_f32_e32 v84, v84
	v_exp_f32_e32 v85, v85
	v_mfma_f32_32x32x16_bf16 v[32:47], v[152:155], v[120:123], v[32:47]
	ds_read_b64_tr_b16 v[116:117], v168 offset:37888
	ds_read_b64_tr_b16 v[118:119], v168 offset:38400
	v_exp_f32_e32 v86, v86
	v_exp_f32_e32 v87, v87
	v_mfma_f32_32x32x16_bf16 v[48:63], v[148:151], v[124:127], v[48:63]
	ds_read_b64_tr_b16 v[120:121], v168 offset:34816
	ds_read_b64_tr_b16 v[122:123], v168 offset:35328
	v_exp_f32_e32 v88, v88
	v_exp_f32_e32 v89, v89
	v_mfma_f32_32x32x16_bf16 v[32:47], v[148:151], v[64:67], v[32:47]
	ds_read_b64_tr_b16 v[124:125], v168 offset:38912
	ds_read_b64_tr_b16 v[126:127], v168 offset:39424
	v_exp_f32_e32 v90, v90
	v_exp_f32_e32 v91, v91
	v_mfma_f32_32x32x16_bf16 v[48:63], v[144:147], v[68:71], v[48:63]
	ds_read_b64_tr_b16 v[64:65], v168 offset:35840
	ds_read_b64_tr_b16 v[66:67], v168 offset:36352
	v_exp_f32_e32 v92, v92
	v_exp_f32_e32 v93, v93
	v_mfma_f32_32x32x16_bf16 v[32:47], v[144:147], v[72:75], v[32:47]
	ds_read_b64_tr_b16 v[68:69], v168 offset:39936
	ds_read_b64_tr_b16 v[70:71], v168 offset:40448
	v_exp_f32_e32 v94, v94
	v_exp_f32_e32 v95, v95
	s_waitcnt lgkmcnt(14)
	v_mfma_f32_32x32x16_bf16 v[16:31], v[156:159], v[76:79], v[16:31]
	v_exp_f32_e32 v96, v96
	v_exp_f32_e32 v97, v97
	s_waitcnt lgkmcnt(12)
; #define SBAR() __builtin_amdgcn_sched_barrier(0)
;   #define RESC() do{ if(!NOMAX&&resc){ asm volatile("s_waitcnt lgkmcnt(0)":::"memory"); \
;       _Pragma("unroll") for(int d_=0;d_<2*VM;++d_) _Pragma("unroll") for(int r=0;r<16;++r)o[d_][r]*=wsf[crow(r,hi)]; } }while(0)
;   #define PKW(P,B) cvtpk_s(P[B],P[B+1])
; template<int THRL,int VM,bool NOMAX> __device__ __forceinline__ void attn_unit(const bf16*Qb,const bf16*__restrict__ Kh,const bf16*__restrict__ Vh,bf16*Ob,const int NT,const int sp,float*wscr,char*shm){
;     ...
;   STEP(pB0,pB1,pA0,pA1,NT-1,false,false,false); RESC();
;   { float sacc=pB0[0]+pB0[1]; _Pragma("unroll") for(int r=2;r<16;++r)sacc+=pB0[r]; _Pragma("unroll") for(int r=0;r<16;++r)sacc+=pB1[r]; l_reg+=sacc;
;     pw0=(u32x4){PKW(pB0,0),PKW(pB0,2),PKW(pB0,4),PKW(pB0,6)};pw1=(u32x4){PKW(pB0,8),PKW(pB0,10),PKW(pB0,12),PKW(pB0,14)};pw2=(u32x4){PKW(pB1,0),PKW(pB1,2),PKW(pB1,4),PKW(pB1,6)};pw3=(u32x4){PKW(pB1,8),PKW(pB1,10),PKW(pB1,12),PKW(pB1,14)};
;     SBAR(); pv(o,vb0+VM*sl_cur,PAF(0),PAF(1),PAF(2),PAF(3)); if constexpr(VM==2) pv(o+2,vb0+VM*sl_cur+8192,PAF(0),PAF(1),PAF(2),PAF(3)); }
;     ...
;   {auto rr=__builtin_amdgcn_permlane32_swap(__float_as_uint(l_reg),__float_as_uint(l_reg),false,false);l_reg=__uint_as_float(rr[0])+__uint_as_float(rr[1]);}
;   if(hi==0)wsf[32+r32]=l_reg;asm volatile("s_waitcnt lgkmcnt(0)":::"memory");
	v_mfma_f32_32x32x16_bf16 v[0:15], v[156:159], v[128:131], v[0:15]
	v_exp_f32_e32 v98, v98
	v_exp_f32_e32 v99, v99
	s_waitcnt lgkmcnt(10)
	v_mfma_f32_32x32x16_bf16 v[16:31], v[152:155], v[112:115], v[16:31]
	v_exp_f32_e32 v100, v100
	v_exp_f32_e32 v101, v101
	s_waitcnt lgkmcnt(8)
	v_mfma_f32_32x32x16_bf16 v[0:15], v[152:155], v[116:119], v[0:15]
	v_exp_f32_e32 v102, v102
	v_exp_f32_e32 v103, v103
	s_waitcnt lgkmcnt(6)
	v_mfma_f32_32x32x16_bf16 v[16:31], v[148:151], v[120:123], v[16:31]
	v_exp_f32_e32 v104, v104
	v_exp_f32_e32 v105, v105
	s_waitcnt lgkmcnt(4)
	v_mfma_f32_32x32x16_bf16 v[0:15], v[148:151], v[124:127], v[0:15]
	v_exp_f32_e32 v106, v106
	v_exp_f32_e32 v107, v107
	s_waitcnt lgkmcnt(2)
	v_mfma_f32_32x32x16_bf16 v[16:31], v[144:147], v[64:67], v[16:31]
	v_exp_f32_e32 v108, v108
	v_exp_f32_e32 v109, v109
	s_waitcnt lgkmcnt(0)
	v_mfma_f32_32x32x16_bf16 v[0:15], v[144:147], v[68:71], v[0:15]
	v_exp_f32_e32 v110, v110
	v_exp_f32_e32 v111, v111
	v_add_f32_e32 v64, v80, v81
	v_add_f32_e32 v64, v82, v64
	v_add_f32_e32 v64, v83, v64
	v_add_f32_e32 v64, v84, v64
	v_add_f32_e32 v64, v85, v64
	v_add_f32_e32 v64, v86, v64
	v_add_f32_e32 v64, v87, v64
	v_add_f32_e32 v64, v88, v64
	v_add_f32_e32 v64, v89, v64
	v_add_f32_e32 v64, v90, v64
	v_add_f32_e32 v64, v91, v64
	v_add_f32_e32 v64, v92, v64
	v_add_f32_e32 v64, v93, v64
	v_add_f32_e32 v64, v94, v64
	v_add_f32_e32 v64, v95, v64
	v_add_f32_e32 v64, v64, v96
	v_add_f32_e32 v64, v97, v64
	v_add_f32_e32 v64, v98, v64
	v_add_f32_e32 v64, v99, v64
	v_add_f32_e32 v64, v100, v64
	v_add_f32_e32 v64, v101, v64
	v_add_f32_e32 v64, v102, v64
	v_add_f32_e32 v64, v103, v64
	v_add_f32_e32 v64, v104, v64
	v_add_f32_e32 v64, v105, v64
	v_add_f32_e32 v64, v106, v64
	v_add_f32_e32 v64, v107, v64
	v_add_f32_e32 v64, v108, v64
	v_add_f32_e32 v64, v109, v64
	v_add_f32_e32 v64, v110, v64
	v_add_f32_e32 v64, v111, v64
	v_add_f32_e32 v65, v174, v136
	v_add_f32_e32 v64, v65, v64
	v_cvt_pk_bf16_f32 v66, v80, v81
	v_cvt_pk_bf16_f32 v67, v82, v83
	v_cvt_pk_bf16_f32 v68, v84, v85
	v_cvt_pk_bf16_f32 v69, v86, v87
	v_cvt_pk_bf16_f32 v70, v88, v89
	v_cvt_pk_bf16_f32 v71, v90, v91
	v_cvt_pk_bf16_f32 v72, v92, v93
	v_cvt_pk_bf16_f32 v73, v94, v95
	v_cvt_pk_bf16_f32 v74, v96, v97
	v_cvt_pk_bf16_f32 v75, v98, v99
	v_cvt_pk_bf16_f32 v76, v100, v101
	v_cvt_pk_bf16_f32 v77, v102, v103
	v_cvt_pk_bf16_f32 v78, v104, v105
	v_cvt_pk_bf16_f32 v79, v106, v107
	v_cvt_pk_bf16_f32 v80, v108, v109
	v_cvt_pk_bf16_f32 v81, v110, v111
	v_add_u32_e32 v65, 0x4000, v176
	ds_read_b64_tr_b16 v[82:83],v65 offset:0
	ds_read_b64_tr_b16 v[84:85],v65 offset:512
	ds_read_b64_tr_b16 v[86:87],v65 offset:1024
	ds_read_b64_tr_b16 v[88:89],v65 offset:1536
	ds_read_b64_tr_b16 v[90:91],v65 offset:2048
	ds_read_b64_tr_b16 v[92:93],v65 offset:2560
	ds_read_b64_tr_b16 v[94:95],v65 offset:3072
	ds_read_b64_tr_b16 v[96:97],v65 offset:3584
	s_waitcnt lgkmcnt(0)
	s_nop 0
	v_mfma_f32_32x32x16_bf16 v[48:63], v[66:69], v[82:85], v[48:63]
	ds_read_b64_tr_b16 v[82:83],v65 offset:4096
	ds_read_b64_tr_b16 v[84:85],v65 offset:4608
	v_mfma_f32_32x32x16_bf16 v[48:63], v[70:73], v[86:89], v[48:63]
	ds_read_b64_tr_b16 v[86:87],v65 offset:5120
	ds_read_b64_tr_b16 v[88:89],v65 offset:5632
	v_mfma_f32_32x32x16_bf16 v[48:63], v[74:77], v[90:93], v[48:63]
	ds_read_b64_tr_b16 v[90:91],v65 offset:6144
	ds_read_b64_tr_b16 v[92:93],v65 offset:6656
	ds_read_b64_tr_b16 v[98:99],v65 offset:7168
	ds_read_b64_tr_b16 v[100:101],v65 offset:7680
	s_waitcnt lgkmcnt(0)
	v_mfma_f32_32x32x16_bf16 v[48:63], v[78:81], v[94:97], v[48:63]
	v_mfma_f32_32x32x16_bf16 v[32:47], v[66:69], v[82:85], v[32:47]
	v_add_u32_e32 v65, 0x6000, v176
	ds_read_b64_tr_b16 v[82:83],v65 offset:0
	ds_read_b64_tr_b16 v[84:85],v65 offset:512
	v_mfma_f32_32x32x16_bf16 v[32:47], v[70:73], v[86:89], v[32:47]
	ds_read_b64_tr_b16 v[86:87],v65 offset:1024
	ds_read_b64_tr_b16 v[88:89],v65 offset:1536
	v_mfma_f32_32x32x16_bf16 v[32:47], v[74:77], v[90:93], v[32:47]
	ds_read_b64_tr_b16 v[90:91],v65 offset:2048
	ds_read_b64_tr_b16 v[92:93],v65 offset:2560
	ds_read_b64_tr_b16 v[94:95],v65 offset:3072
	ds_read_b64_tr_b16 v[96:97],v65 offset:3584
	s_waitcnt lgkmcnt(0)
	v_mfma_f32_32x32x16_bf16 v[32:47], v[78:81], v[98:101], v[32:47]
	v_mfma_f32_32x32x16_bf16 v[16:31], v[66:69], v[82:85], v[16:31]
	ds_read_b64_tr_b16 v[82:83],v65 offset:4096
	ds_read_b64_tr_b16 v[84:85],v65 offset:4608
	v_mfma_f32_32x32x16_bf16 v[16:31], v[70:73], v[86:89], v[16:31]
	ds_read_b64_tr_b16 v[86:87],v65 offset:5120
	ds_read_b64_tr_b16 v[88:89],v65 offset:5632
	v_mfma_f32_32x32x16_bf16 v[16:31], v[74:77], v[90:93], v[16:31]
	ds_read_b64_tr_b16 v[90:91],v65 offset:6144
	ds_read_b64_tr_b16 v[92:93],v65 offset:6656
	ds_read_b64_tr_b16 v[98:99],v65 offset:7168
	ds_read_b64_tr_b16 v[100:101],v65 offset:7680
	s_waitcnt lgkmcnt(0)
	v_mfma_f32_32x32x16_bf16 v[16:31], v[78:81], v[94:97], v[16:31]
	v_mfma_f32_32x32x16_bf16 v[0:15], v[66:69], v[82:85], v[0:15]
	v_mov_b32_e32 v65, v64
	s_nop 1
	v_permlane32_swap_b32_e32 v64, v65
	v_cmp_gt_u32_e32 vcc, 32, v187
	v_mfma_f32_32x32x16_bf16 v[0:15], v[70:73], v[86:89], v[0:15]
	v_mfma_f32_32x32x16_bf16 v[0:15], v[74:77], v[90:93], v[0:15]
	v_mfma_f32_32x32x16_bf16 v[0:15], v[78:81], v[98:101], v[0:15]
	s_and_saveexec_b64 s[16:17], vcc
	s_cbranch_execz .LBB0_859
	v_add_f32_e32 v64, v64, v65
	v_lshl_add_u32 v65, v186, 2, s34
	ds_write_b32 v65, v64 offset:128
	s_branch .LBB0_859

.LBB0_874:
	v_mfma_f32_32x32x16_bf16 v[112:127], v[100:103], v[218:221], 0
	v_lshl_add_u32 v206, s89, 1, v188
	ds_read_b64_tr_b16 v[194:195], v206 offset:24576
	ds_read_b64_tr_b16 v[196:197], v206 offset:25088
	v_add_f32_e32 v108, v80, v81
	v_add_f32_e32 v108, v82, v108
	v_add_f32_e32 v108, v83, v108
	v_add_f32_e32 v108, v84, v108
	v_add_f32_e32 v108, v85, v108
	v_cvt_pk_bf16_f32 v156, v80, v81
	v_cvt_pk_bf16_f32 v157, v82, v83
	ds_read_b64_tr_b16 v[80:81], v206 offset:28672
	ds_read_b64_tr_b16 v[82:83], v206 offset:29184
	v_add_f32_e32 v104, v86, v108
	v_add_f32_e32 v104, v87, v104
	v_add_f32_e32 v104, v88, v104
	v_add_f32_e32 v144, v89, v104
	v_mfma_f32_32x32x16_bf16 v[96:111], v[96:99], v[218:221], 0
	v_cvt_pk_bf16_f32 v158, v84, v85
	v_cvt_pk_bf16_f32 v159, v86, v87
	ds_read_b64_tr_b16 v[84:85], v206 offset:25600
	ds_read_b64_tr_b16 v[86:87], v206 offset:26112
	v_add_f32_e32 v144, v90, v144
	v_add_f32_e32 v144, v91, v144
	v_add_f32_e32 v144, v92, v144
	v_add_f32_e32 v144, v93, v144
	v_cvt_pk_bf16_f32 v152, v88, v89
	v_cvt_pk_bf16_f32 v153, v90, v91
	v_mfma_f32_32x32x16_bf16 v[112:127], v[164:167], v[222:225], v[112:127]
	ds_read_b64_tr_b16 v[88:89], v206 offset:29696
	ds_read_b64_tr_b16 v[90:91], v206 offset:30208
	v_add_f32_e32 v144, v94, v144
	v_add_f32_e32 v144, v95, v144
	v_add_f32_e32 v144, v64, v144
	v_add_f32_e32 v144, v65, v144
	v_mfma_f32_32x32x16_bf16 v[96:111], v[160:163], v[222:225], v[96:111]
	v_cvt_pk_bf16_f32 v154, v92, v93
	v_cvt_pk_bf16_f32 v155, v94, v95
	ds_read_b64_tr_b16 v[92:93], v206 offset:26624
	ds_read_b64_tr_b16 v[94:95], v206 offset:27136
	v_add_f32_e32 v144, v66, v144
	v_add_f32_e32 v144, v67, v144
	v_add_f32_e32 v144, v68, v144
	v_add_f32_e32 v144, v69, v144
	v_cvt_pk_bf16_f32 v148, v64, v65
	v_cvt_pk_bf16_f32 v149, v66, v67
	v_mfma_f32_32x32x16_bf16 v[112:127], v[140:143], v[226:229], v[112:127]
	ds_read_b64_tr_b16 v[198:199], v206 offset:30720
	ds_read_b64_tr_b16 v[200:201], v206 offset:31232
	v_add_f32_e32 v140, v70, v144
	v_add_f32_e32 v140, v71, v140
	v_add_f32_e32 v140, v72, v140
	v_add_f32_e32 v140, v73, v140
	v_mfma_f32_32x32x16_bf16 v[96:111], v[136:139], v[226:229], v[96:111]
	v_cvt_pk_bf16_f32 v150, v68, v69
	v_cvt_pk_bf16_f32 v151, v70, v71
	ds_read_b64_tr_b16 v[202:203], v206 offset:27648
	ds_read_b64_tr_b16 v[204:205], v206 offset:28160
	v_add_f32_e32 v68, v74, v140
	v_add_f32_e32 v68, v75, v68
	v_add_f32_e32 v68, v76, v68
	v_add_f32_e32 v68, v77, v68
	v_cvt_pk_bf16_f32 v144, v72, v73
	v_cvt_pk_bf16_f32 v145, v74, v75
	v_mfma_f32_32x32x16_bf16 v[112:127], v[132:135], v[230:233], v[112:127]
	ds_read_b64_tr_b16 v[72:73], v206 offset:31744
	ds_read_b64_tr_b16 v[74:75], v206 offset:32256
	v_add_f32_e32 v68, v78, v68
	v_add_f32_e32 v68, v79, v68
	v_add_f32_e32 v68, 0, v68
	v_cvt_pk_bf16_f32 v146, v76, v77
	v_mfma_f32_32x32x16_bf16 v[96:111], v[128:131], v[230:233], v[96:111]
	v_cvt_pk_bf16_f32 v147, v78, v79
	s_add_i32 s88, s87, s17
	v_lshl_add_u64 v[64:65], v[180:181], 0, s[56:57]
	s_mov_b32 s89, m0
	s_mov_b32 m0, s88
	s_nop 0
	global_load_lds_dwordx4 v[64:65], off
	s_mov_b32 m0, s89
	s_lshl_b32 s88, s86, 1
	v_lshl_add_u64 v[64:65], v[178:179], 0, s[56:57]
	s_add_i32 s88, s88, s16
	s_mov_b32 s89, m0
	s_mov_b32 m0, s88
	s_nop 0
	global_load_lds_dwordx4 v[64:65], off
	s_mov_b32 m0, s89
	v_lshl_add_u64 v[64:65], v[176:177], 0, s[56:57]
	s_addk_i32 s88, 0x2000
	s_mov_b32 s89, m0
	s_mov_b32 m0, s88
	s_nop 0
	global_load_lds_dwordx4 v[64:65], off
	s_mov_b32 m0, s89
	v_add_f32_e32 v193, v193, v68
	v_add_u32_e32 v242, s86, v234
	v_add_u32_e32 v243, s86, v235
	v_add_u32_e32 v244, s86, v236
	v_add_u32_e32 v245, s86, v237
	s_waitcnt lgkmcnt(12)
	v_mfma_f32_32x32x16_bf16 v[48:63], v[156:159], v[194:197], v[48:63]
	ds_read_b64_tr_b16 v[76:77], v206 offset:32768
	ds_read_b64_tr_b16 v[78:79], v206 offset:33280
	v_exp_f32_e32 v112, v112
	v_exp_f32_e32 v113, v113
	ds_read_b128 v[68:71], v242
	v_mfma_f32_32x32x16_bf16 v[32:47], v[156:159], v[80:83], v[32:47]
	ds_read_b64_tr_b16 v[194:195], v206 offset:36864
	ds_read_b64_tr_b16 v[196:197], v206 offset:37376
	v_exp_f32_e32 v114, v114
	v_exp_f32_e32 v115, v115
	ds_read_b128 v[64:67], v242 offset:4096
	s_waitcnt lgkmcnt(14)
	v_mfma_f32_32x32x16_bf16 v[48:63], v[152:155], v[84:87], v[48:63]
	ds_read_b64_tr_b16 v[80:81], v206 offset:33792
	ds_read_b64_tr_b16 v[82:83], v206 offset:34304
	v_exp_f32_e32 v116, v116
	v_exp_f32_e32 v117, v117
	ds_read_b128 v[164:167], v243
	v_mfma_f32_32x32x16_bf16 v[32:47], v[152:155], v[88:91], v[32:47]
	ds_read_b64_tr_b16 v[84:85], v206 offset:37888
	ds_read_b64_tr_b16 v[86:87], v206 offset:38400
	v_exp_f32_e32 v118, v118
	v_exp_f32_e32 v119, v119
	ds_read_b128 v[140:143], v243 offset:4096
	s_waitcnt lgkmcnt(14)
	v_mfma_f32_32x32x16_bf16 v[48:63], v[148:151], v[92:95], v[48:63]
	ds_read_b64_tr_b16 v[88:89], v206 offset:34816
	ds_read_b64_tr_b16 v[90:91], v206 offset:35328
	v_exp_f32_e32 v120, v120
	v_exp_f32_e32 v121, v121
	ds_read_b128 v[160:163], v244
	v_mfma_f32_32x32x16_bf16 v[32:47], v[148:151], v[198:201], v[32:47]
	ds_read_b64_tr_b16 v[92:93], v206 offset:38912
	ds_read_b64_tr_b16 v[94:95], v206 offset:39424
	v_exp_f32_e32 v122, v122
	v_exp_f32_e32 v123, v123
	ds_read_b128 v[132:135], v244 offset:4096
	s_waitcnt lgkmcnt(14)
	v_mfma_f32_32x32x16_bf16 v[48:63], v[144:147], v[202:205], v[48:63]
	ds_read_b64_tr_b16 v[198:199], v206 offset:35840
	ds_read_b64_tr_b16 v[200:201], v206 offset:36352
	v_exp_f32_e32 v124, v124
	v_exp_f32_e32 v125, v125
	ds_read_b128 v[136:139], v245
	v_mfma_f32_32x32x16_bf16 v[32:47], v[144:147], v[72:75], v[32:47]
	ds_read_b64_tr_b16 v[202:203], v206 offset:39936
	ds_read_b64_tr_b16 v[204:205], v206 offset:40448
	v_exp_f32_e32 v126, v126
	v_exp_f32_e32 v127, v127
	ds_read_b128 v[128:131], v245 offset:4096
	s_waitcnt lgkmcnt(14)
	v_mfma_f32_32x32x16_bf16 v[16:31], v[156:159], v[76:79], v[16:31]
	v_exp_f32_e32 v96, v96
	v_exp_f32_e32 v97, v97
	v_mfma_f32_32x32x16_bf16 v[0:15], v[156:159], v[194:197], v[0:15]
	v_exp_f32_e32 v98, v98
	v_exp_f32_e32 v99, v99
	v_mfma_f32_32x32x16_bf16 v[16:31], v[152:155], v[80:83], v[16:31]
	v_exp_f32_e32 v100, v100
	v_exp_f32_e32 v101, v101
	s_waitcnt lgkmcnt(12)
	v_mfma_f32_32x32x16_bf16 v[0:15], v[152:155], v[84:87], v[0:15]
	v_exp_f32_e32 v102, v102
	v_exp_f32_e32 v103, v103
	s_waitcnt lgkmcnt(8)
	v_mfma_f32_32x32x16_bf16 v[16:31], v[148:151], v[88:91], v[16:31]
	v_exp_f32_e32 v104, v104
	v_exp_f32_e32 v105, v105
	s_waitcnt lgkmcnt(4)
	v_mfma_f32_32x32x16_bf16 v[0:15], v[148:151], v[92:95], v[0:15]
	v_exp_f32_e32 v106, v106
	v_exp_f32_e32 v107, v107
	s_waitcnt lgkmcnt(2)
	v_mfma_f32_32x32x16_bf16 v[16:31], v[144:147], v[198:201], v[16:31]
	v_exp_f32_e32 v108, v108
	v_exp_f32_e32 v109, v109
	s_waitcnt lgkmcnt(0)
	v_mfma_f32_32x32x16_bf16 v[0:15], v[144:147], v[202:205], v[0:15]
	v_exp_f32_e32 v110, v110
	v_exp_f32_e32 v111, v111
	s_waitcnt vmcnt(3) lgkmcnt(0)
	s_barrier
	v_mfma_f32_32x32x16_bf16 v[80:95], v[68:71], v[218:221], 0
	s_add_i32 s88, s86, 0x2000
	s_cmpk_lg_i32 s86, 0x4000
	s_cselect_b32 s88, s88, 0
	v_lshl_add_u32 v206, s87, 1, v188
	ds_read_b64_tr_b16 v[194:195], v206 offset:24576
	ds_read_b64_tr_b16 v[196:197], v206 offset:25088
	v_add_f32_e32 v76, v112, v113
	v_add_f32_e32 v76, v114, v76
	v_add_f32_e32 v76, v115, v76
	v_add_f32_e32 v76, v116, v76
	v_add_f32_e32 v76, v117, v76
	v_cvt_pk_bf16_f32 v156, v112, v113
	v_cvt_pk_bf16_f32 v157, v114, v115
	ds_read_b64_tr_b16 v[112:113], v206 offset:28672
	ds_read_b64_tr_b16 v[114:115], v206 offset:29184
	v_add_f32_e32 v72, v118, v76
	v_add_f32_e32 v72, v119, v72
	v_add_f32_e32 v72, v120, v72
	v_add_f32_e32 v144, v121, v72
	v_mfma_f32_32x32x16_bf16 v[64:79], v[64:67], v[218:221], 0
	v_cvt_pk_bf16_f32 v158, v116, v117
	v_cvt_pk_bf16_f32 v159, v118, v119
	ds_read_b64_tr_b16 v[116:117], v206 offset:25600
	ds_read_b64_tr_b16 v[118:119], v206 offset:26112
	v_add_f32_e32 v144, v122, v144
	v_add_f32_e32 v144, v123, v144
	v_add_f32_e32 v144, v124, v144
	v_add_f32_e32 v144, v125, v144
	v_mfma_f32_32x32x16_bf16 v[80:95], v[164:167], v[222:225], v[80:95]
	v_cvt_pk_bf16_f32 v152, v120, v121
	v_cvt_pk_bf16_f32 v153, v122, v123
	ds_read_b64_tr_b16 v[120:121], v206 offset:29696
	ds_read_b64_tr_b16 v[122:123], v206 offset:30208
	v_add_f32_e32 v144, v126, v144
	v_add_f32_e32 v144, v127, v144
	v_add_f32_e32 v144, v96, v144
	v_add_f32_e32 v144, v97, v144
	v_mfma_f32_32x32x16_bf16 v[64:79], v[140:143], v[222:225], v[64:79]
	v_cvt_pk_bf16_f32 v154, v124, v125
	v_cvt_pk_bf16_f32 v155, v126, v127
	ds_read_b64_tr_b16 v[124:125], v206 offset:26624
	ds_read_b64_tr_b16 v[126:127], v206 offset:27136
	v_add_f32_e32 v144, v98, v144
	v_add_f32_e32 v144, v99, v144
	v_add_f32_e32 v144, v100, v144
	v_add_f32_e32 v144, v101, v144
	v_mfma_f32_32x32x16_bf16 v[80:95], v[160:163], v[226:229], v[80:95]
	v_cvt_pk_bf16_f32 v148, v96, v97
	v_cvt_pk_bf16_f32 v149, v98, v99
	ds_read_b64_tr_b16 v[198:199], v206 offset:30720
	ds_read_b64_tr_b16 v[200:201], v206 offset:31232
	v_add_f32_e32 v140, v102, v144
	v_add_f32_e32 v140, v103, v140
	v_add_f32_e32 v140, v104, v140
	v_add_f32_e32 v140, v105, v140
	v_mfma_f32_32x32x16_bf16 v[64:79], v[132:135], v[226:229], v[64:79]
	v_cvt_pk_bf16_f32 v150, v100, v101
	v_cvt_pk_bf16_f32 v151, v102, v103
	ds_read_b64_tr_b16 v[202:203], v206 offset:27648
	ds_read_b64_tr_b16 v[204:205], v206 offset:28160
	v_add_f32_e32 v100, v106, v140
	v_add_f32_e32 v100, v107, v100
	v_add_f32_e32 v100, v108, v100
	v_add_f32_e32 v100, v109, v100
	v_mfma_f32_32x32x16_bf16 v[80:95], v[136:139], v[230:233], v[80:95]
	v_cvt_pk_bf16_f32 v144, v104, v105
	v_cvt_pk_bf16_f32 v145, v106, v107
	ds_read_b64_tr_b16 v[104:105], v206 offset:31744
	ds_read_b64_tr_b16 v[106:107], v206 offset:32256
	v_add_f32_e32 v100, v110, v100
	v_add_f32_e32 v100, v111, v100
	v_add_f32_e32 v100, 0, v100
	v_cvt_pk_bf16_f32 v146, v108, v109
	v_mfma_f32_32x32x16_bf16 v[64:79], v[128:131], v[230:233], v[64:79]
	v_cvt_pk_bf16_f32 v147, v110, v111
	s_add_i32 s87, s86, s17
	s_mov_b32 s89, m0
	s_mov_b32 m0, s87
	s_nop 0
	global_load_lds_dwordx4 v[180:181], off
	s_mov_b32 m0, s89
	s_lshl_b32 s87, s88, 1
	s_add_i32 s87, s87, s16
	s_mov_b32 s89, m0
	s_mov_b32 m0, s87
	s_nop 0
	global_load_lds_dwordx4 v[178:179], off
	s_mov_b32 m0, s89
	s_addk_i32 s87, 0x2000
	s_mov_b32 s89, m0
	s_mov_b32 m0, s87
	s_nop 0
	global_load_lds_dwordx4 v[176:177], off
	s_mov_b32 m0, s89
	v_add_f32_e32 v193, v193, v100
	v_add_u32_e32 v242, s88, v234
	v_add_u32_e32 v243, s88, v235
	v_add_u32_e32 v244, s88, v236
	v_add_u32_e32 v245, s88, v237
	s_waitcnt lgkmcnt(12)
	v_mfma_f32_32x32x16_bf16 v[48:63], v[156:159], v[194:197], v[48:63]
	ds_read_b64_tr_b16 v[108:109], v206 offset:32768
	ds_read_b64_tr_b16 v[110:111], v206 offset:33280
	v_exp_f32_e32 v80, v80
	v_exp_f32_e32 v81, v81
	ds_read_b128 v[100:103], v242
	v_mfma_f32_32x32x16_bf16 v[32:47], v[156:159], v[112:115], v[32:47]
	ds_read_b64_tr_b16 v[194:195], v206 offset:36864
	ds_read_b64_tr_b16 v[196:197], v206 offset:37376
	v_exp_f32_e32 v82, v82
	v_exp_f32_e32 v83, v83
	ds_read_b128 v[96:99], v242 offset:4096
	s_waitcnt lgkmcnt(14)
	v_mfma_f32_32x32x16_bf16 v[48:63], v[152:155], v[116:119], v[48:63]
	ds_read_b64_tr_b16 v[112:113], v206 offset:33792
	ds_read_b64_tr_b16 v[114:115], v206 offset:34304
	v_exp_f32_e32 v84, v84
	v_exp_f32_e32 v85, v85
	ds_read_b128 v[164:167], v243
	v_mfma_f32_32x32x16_bf16 v[32:47], v[152:155], v[120:123], v[32:47]
	ds_read_b64_tr_b16 v[116:117], v206 offset:37888
	ds_read_b64_tr_b16 v[118:119], v206 offset:38400
	v_exp_f32_e32 v86, v86
	v_exp_f32_e32 v87, v87
	ds_read_b128 v[160:163], v243 offset:4096
	s_waitcnt lgkmcnt(14)
	v_mfma_f32_32x32x16_bf16 v[48:63], v[148:151], v[124:127], v[48:63]
	ds_read_b64_tr_b16 v[120:121], v206 offset:34816
	ds_read_b64_tr_b16 v[122:123], v206 offset:35328
	v_exp_f32_e32 v88, v88
	v_exp_f32_e32 v89, v89
	ds_read_b128 v[140:143], v244
	v_mfma_f32_32x32x16_bf16 v[32:47], v[148:151], v[198:201], v[32:47]
	ds_read_b64_tr_b16 v[124:125], v206 offset:38912
	ds_read_b64_tr_b16 v[126:127], v206 offset:39424
	v_exp_f32_e32 v90, v90
	v_exp_f32_e32 v91, v91
	ds_read_b128 v[136:139], v244 offset:4096
	s_waitcnt lgkmcnt(14)
	v_mfma_f32_32x32x16_bf16 v[48:63], v[144:147], v[202:205], v[48:63]
	ds_read_b64_tr_b16 v[198:199], v206 offset:35840
	ds_read_b64_tr_b16 v[200:201], v206 offset:36352
	v_exp_f32_e32 v92, v92
	v_exp_f32_e32 v93, v93
	ds_read_b128 v[132:135], v245
	v_mfma_f32_32x32x16_bf16 v[32:47], v[144:147], v[104:107], v[32:47]
	ds_read_b64_tr_b16 v[202:203], v206 offset:39936
	ds_read_b64_tr_b16 v[204:205], v206 offset:40448
	v_exp_f32_e32 v94, v94
	v_exp_f32_e32 v95, v95
	ds_read_b128 v[128:131], v245 offset:4096
	s_waitcnt lgkmcnt(14)
; #define WAIT_BAR(N) asm volatile("s_waitcnt vmcnt(" #N ") lgkmcnt(0)\n\ts_barrier":::"memory")
;   #define RESC() do{ if(!NOMAX&&resc){ asm volatile("s_waitcnt lgkmcnt(0)":::"memory"); \
;       _Pragma("unroll") for(int d_=0;d_<2*VM;++d_) _Pragma("unroll") for(int r=0;r<16;++r)o[d_][r]*=wsf[crow(r,hi)]; } }while(0)
;   #define ROT() do{sl_prev=sl_cur;sl_cur=sl_next;sl_next=(sl_next==(NSLOT-1)*SLOTB)?0:sl_next+SLOTB;}while(0)
;   #define ENDW(tt) do{ if((tt)+3<NT){ if constexpr(VM==2){WAIT_BAR(3);}else{WAIT_BAR(2);} } else if((tt)+2<NT){ if constexpr(VM==2){WAIT_BAR(2);}else{WAIT_BAR(1);} } else {WAIT_BAR(0);} }while(0)
; template<int THRL,int VM,bool NOMAX> __device__ __forceinline__ void attn_unit(const bf16*Qb,const bf16*__restrict__ Kh,const bf16*__restrict__ Vh,bf16*Ob,const int NT,const int sp,float*wscr,char*shm){
;     ...
;   int t=1;
;   for(;t+5<NT;t+=2){
;     STEP(pB0,pB1,pA0,pA1,t,true,true,true);     if constexpr(VM==2){WAIT_BAR(3);}else{WAIT_BAR(2);} RESC(); ROT();
;     STEP(pA0,pA1,pB0,pB1,t+1,true,true,true);   if constexpr(VM==2){WAIT_BAR(3);}else{WAIT_BAR(2);} RESC(); ROT();
;   }
;     ...
;   for(;t+1<NT;t+=2){
;     STEP(pB0,pB1,pA0,pA1,t,(t+3<NT),(t+1<NT),(t+1<NT));       ENDW(t);   RESC(); ROT();
;     STEP(pA0,pA1,pB0,pB1,t+1,(t+4<NT),(t+2<NT),(t+2<NT));     ENDW(t+1); RESC(); ROT();
	v_mfma_f32_32x32x16_bf16 v[16:31], v[156:159], v[108:111], v[16:31]
	v_exp_f32_e32 v64, v64
	v_exp_f32_e32 v65, v65
	v_mfma_f32_32x32x16_bf16 v[0:15], v[156:159], v[194:197], v[0:15]
	v_exp_f32_e32 v66, v66
	v_exp_f32_e32 v67, v67
	v_mfma_f32_32x32x16_bf16 v[16:31], v[152:155], v[112:115], v[16:31]
	v_exp_f32_e32 v68, v68
	v_exp_f32_e32 v69, v69
	s_waitcnt lgkmcnt(12)
	v_mfma_f32_32x32x16_bf16 v[0:15], v[152:155], v[116:119], v[0:15]
	v_exp_f32_e32 v70, v70
	v_exp_f32_e32 v71, v71
	s_waitcnt lgkmcnt(8)
	v_mfma_f32_32x32x16_bf16 v[16:31], v[148:151], v[120:123], v[16:31]
	v_exp_f32_e32 v72, v72
	v_exp_f32_e32 v73, v73
	s_waitcnt lgkmcnt(4)
	v_mfma_f32_32x32x16_bf16 v[0:15], v[148:151], v[124:127], v[0:15]
	v_exp_f32_e32 v74, v74
	v_exp_f32_e32 v75, v75
	s_waitcnt lgkmcnt(2)
	v_mfma_f32_32x32x16_bf16 v[16:31], v[144:147], v[198:201], v[16:31]
	v_exp_f32_e32 v76, v76
	v_exp_f32_e32 v77, v77
	s_waitcnt lgkmcnt(0)
	v_mfma_f32_32x32x16_bf16 v[0:15], v[144:147], v[202:205], v[0:15]
	v_exp_f32_e32 v78, v78
	v_exp_f32_e32 v79, v79
	s_add_i32 s90, s88, 0x2000
	s_cmpk_lg_i32 s88, 0x4000
	s_mov_b32 s89, s86
	s_cselect_b32 s86, s90, 0
	s_add_i32 s85, s85, 2
	v_lshl_add_u64 v[176:177], v[176:177], 0, s[58:59]
	v_lshl_add_u64 v[178:179], v[178:179], 0, s[58:59]
	v_lshl_add_u64 v[180:181], v[180:181], 0, s[58:59]
	s_mov_b32 s87, s88
	s_cmp_lt_u32 s85, 57
	s_waitcnt vmcnt(3) lgkmcnt(0)
	s_barrier
	s_cbranch_scc1 .LBB0_874
	s_and_b32 s34, s34, 0x3fffffc0
	s_lshl_b32 s34, s34, 2
	s_add_i32 s34, s34, 0
	s_add_i32 s34, s34, 0x12000
	s_cmp_lg_u32 0, -1
	s_cselect_b32 s85, 0, 0
	s_add_i32 s86, s85, 0x6000
	v_add_u32_e32 v104, s86, v191
	v_add3_u32 v176, v104, v190, v192
	v_add_u32_e32 v177, 0x6000, v188
	ds_read_b64_tr_b16 v[178:179], v188 offset:40960
	ds_read_b64_tr_b16 v[180:181], v188 offset:41472
	v_add_f32_e32 v108, v80, v81
	ds_read_b128 v[104:107], v168
	v_add_f32_e32 v108, v82, v108
	v_add_f32_e32 v108, v83, v108
	v_add_f32_e32 v108, v84, v108
	v_add_f32_e32 v108, v85, v108
	v_cvt_pk_bf16_f32 v156, v80, v81
	v_cvt_pk_bf16_f32 v157, v82, v83
	s_waitcnt lgkmcnt(0)
	v_mfma_f32_32x32x16_bf16 v[112:127], v[100:103], v[104:107], 0
	ds_read_b64_tr_b16 v[80:81], v188 offset:45056
	ds_read_b64_tr_b16 v[82:83], v188 offset:45568
	ds_read_b128 v[100:103], v168
	v_add_f32_e32 v104, v86, v108
	v_add_f32_e32 v104, v87, v104
	v_add_f32_e32 v104, v88, v104
	v_add_f32_e32 v144, v89, v104
	v_cvt_pk_bf16_f32 v158, v84, v85
	v_cvt_pk_bf16_f32 v159, v86, v87
	s_waitcnt lgkmcnt(0)
	v_mfma_f32_32x32x16_bf16 v[96:111], v[96:99], v[100:103], 0
	ds_read_b64_tr_b16 v[84:85], v188 offset:41984
	ds_read_b64_tr_b16 v[86:87], v188 offset:42496
	ds_read_b128 v[194:197], v168 offset:1024
	v_add_f32_e32 v144, v90, v144
	v_add_f32_e32 v144, v91, v144
	v_add_f32_e32 v144, v92, v144
	v_add_f32_e32 v144, v93, v144
	v_cvt_pk_bf16_f32 v152, v88, v89
	v_cvt_pk_bf16_f32 v153, v90, v91
	s_waitcnt lgkmcnt(0)
	v_mfma_f32_32x32x16_bf16 v[112:127], v[164:167], v[194:197], v[112:127]
	ds_read_b64_tr_b16 v[88:89], v188 offset:46080
	ds_read_b64_tr_b16 v[90:91], v188 offset:46592
	ds_read_b128 v[164:167], v168 offset:1024
	v_add_f32_e32 v144, v94, v144
	v_add_f32_e32 v144, v95, v144
	v_add_f32_e32 v144, v64, v144
	v_add_f32_e32 v144, v65, v144
	v_cvt_pk_bf16_f32 v154, v92, v93
	v_cvt_pk_bf16_f32 v155, v94, v95
	s_waitcnt lgkmcnt(0)
	v_mfma_f32_32x32x16_bf16 v[96:111], v[160:163], v[164:167], v[96:111]
	ds_read_b64_tr_b16 v[194:195], v188 offset:43008
	ds_read_b64_tr_b16 v[196:197], v188 offset:43520
	ds_read_b128 v[92:95], v168 offset:2048
	v_add_f32_e32 v144, v66, v144
	v_add_f32_e32 v144, v67, v144
	v_add_f32_e32 v144, v68, v144
	v_add_f32_e32 v144, v69, v144
	v_cvt_pk_bf16_f32 v148, v64, v65
	v_cvt_pk_bf16_f32 v149, v66, v67
	s_waitcnt lgkmcnt(0)
	v_mfma_f32_32x32x16_bf16 v[112:127], v[140:143], v[92:95], v[112:127]
	ds_read_b64_tr_b16 v[140:141], v188 offset:47104
	ds_read_b64_tr_b16 v[142:143], v188 offset:47616
	ds_read_b128 v[64:67], v168 offset:2048
	v_add_f32_e32 v92, v70, v144
	v_add_f32_e32 v92, v71, v92
	v_add_f32_e32 v92, v72, v92
	v_add_f32_e32 v92, v73, v92
	v_cvt_pk_bf16_f32 v150, v68, v69
	v_cvt_pk_bf16_f32 v151, v70, v71
	s_waitcnt lgkmcnt(0)
	v_mfma_f32_32x32x16_bf16 v[96:111], v[136:139], v[64:67], v[96:111]
	ds_read_b64_tr_b16 v[136:137], v188 offset:44032
	ds_read_b64_tr_b16 v[138:139], v188 offset:44544
	ds_read_b128 v[64:67], v168 offset:3072
	v_add_f32_e32 v68, v74, v92
	v_add_f32_e32 v68, v75, v68
	v_add_f32_e32 v68, v76, v68
	v_add_f32_e32 v68, v77, v68
	v_cvt_pk_bf16_f32 v144, v72, v73
	v_cvt_pk_bf16_f32 v145, v74, v75
	s_waitcnt lgkmcnt(0)
	v_mfma_f32_32x32x16_bf16 v[112:127], v[132:135], v[64:67], v[112:127]
	ds_read_b64_tr_b16 v[72:73], v188 offset:48128
	ds_read_b64_tr_b16 v[74:75], v188 offset:48640
	ds_read_b128 v[64:67], v168 offset:3072
	v_add_f32_e32 v68, v78, v68
	v_add_f32_e32 v68, v79, v68
	v_add_f32_e32 v68, 0, v68
	v_cvt_pk_bf16_f32 v146, v76, v77
	v_cvt_pk_bf16_f32 v147, v78, v79
	s_waitcnt lgkmcnt(0)
; #define WAIT_BAR(N) asm volatile("s_waitcnt vmcnt(" #N ") lgkmcnt(0)\n\ts_barrier":::"memory")
;   #define RESC() do{ if(!NOMAX&&resc){ asm volatile("s_waitcnt lgkmcnt(0)":::"memory"); \
;       _Pragma("unroll") for(int d_=0;d_<2*VM;++d_) _Pragma("unroll") for(int r=0;r<16;++r)o[d_][r]*=wsf[crow(r,hi)]; } }while(0)
;   #define ROT() do{sl_prev=sl_cur;sl_cur=sl_next;sl_next=(sl_next==(NSLOT-1)*SLOTB)?0:sl_next+SLOTB;}while(0)
; template<int THRL,int VM,bool NOMAX> __device__ __forceinline__ void attn_unit(const bf16*Qb,const bf16*__restrict__ Kh,const bf16*__restrict__ Vh,bf16*Ob,const int NT,const int sp,float*wscr,char*shm){
;     ...
;   int t=1;
;   for(;t+5<NT;t+=2){
;     STEP(pB0,pB1,pA0,pA1,t,true,true,true);     if constexpr(VM==2){WAIT_BAR(3);}else{WAIT_BAR(2);} RESC(); ROT();
;     STEP(pA0,pA1,pB0,pB1,t+1,true,true,true);   if constexpr(VM==2){WAIT_BAR(3);}else{WAIT_BAR(2);} RESC(); ROT();
	v_mfma_f32_32x32x16_bf16 v[96:111], v[128:131], v[64:67], v[96:111]
	s_add_i32 s85, s85, s35
	v_lshl_add_u64 v[64:65], v[174:175], 0, s[60:61]
	s_add_i32 s35, s85, 0x4000
	s_mov_b32 s86, m0
	s_mov_b32 m0, s35
	s_nop 0
	global_load_lds_dwordx4 v[64:65], off
	s_mov_b32 m0, s86
	v_lshl_add_u64 v[64:65], v[170:171], 0, s[62:63]
	s_mov_b32 s35, m0
	s_mov_b32 m0, s16
	s_nop 0
	global_load_lds_dwordx4 v[64:65], off
	s_mov_b32 m0, s35
	v_lshl_add_u64 v[64:65], v[172:173], 0, s[62:63]
	s_add_i32 s35, s16, 0x2000
	s_mov_b32 s86, m0
	s_mov_b32 m0, s35
	s_nop 0
	global_load_lds_dwordx4 v[64:65], off
	s_mov_b32 m0, s86
	v_add_f32_e32 v198, v193, v68
	v_mfma_f32_32x32x16_bf16 v[48:63], v[156:159], v[178:181], v[48:63]
	ds_read_b64_tr_b16 v[76:77], v188 offset:49152
	ds_read_b64_tr_b16 v[78:79], v188 offset:49664
	v_exp_f32_e32 v112, v112
	v_exp_f32_e32 v113, v113
	v_mfma_f32_32x32x16_bf16 v[32:47], v[156:159], v[80:83], v[32:47]
	ds_read_b64_tr_b16 v[128:129], v188 offset:53248
	ds_read_b64_tr_b16 v[130:131], v188 offset:53760
	v_exp_f32_e32 v114, v114
	v_exp_f32_e32 v115, v115
	ds_read_b128 v[68:71], v234
	ds_read_b128 v[64:67], v234 offset:4096
	v_mfma_f32_32x32x16_bf16 v[48:63], v[152:155], v[84:87], v[48:63]
	ds_read_b64_tr_b16 v[132:133], v188 offset:50176
	ds_read_b64_tr_b16 v[134:135], v188 offset:50688
	v_exp_f32_e32 v116, v116
	v_exp_f32_e32 v117, v117
	ds_read_b128 v[164:167], v235
	ds_read_b128 v[92:95], v235 offset:4096
	v_mfma_f32_32x32x16_bf16 v[32:47], v[152:155], v[88:91], v[32:47]
	ds_read_b64_tr_b16 v[178:179], v188 offset:54272
	ds_read_b64_tr_b16 v[180:181], v188 offset:54784
	v_exp_f32_e32 v118, v118
	v_exp_f32_e32 v119, v119
	ds_read_b128 v[160:163], v236
	ds_read_b128 v[84:87], v236 offset:4096
	v_mfma_f32_32x32x16_bf16 v[48:63], v[148:151], v[194:197], v[48:63]
	ds_read_b64_tr_b16 v[190:191], v188 offset:51200
	ds_read_b64_tr_b16 v[192:193], v188 offset:51712
	v_exp_f32_e32 v120, v120
	v_exp_f32_e32 v121, v121
	ds_read_b128 v[88:91], v237
	ds_read_b128 v[80:83], v237 offset:4096
	v_mfma_f32_32x32x16_bf16 v[32:47], v[148:151], v[140:143], v[32:47]
	ds_read_b64_tr_b16 v[194:195], v188 offset:55296
	ds_read_b64_tr_b16 v[196:197], v188 offset:55808
	v_exp_f32_e32 v122, v122
	v_exp_f32_e32 v123, v123
	v_mfma_f32_32x32x16_bf16 v[48:63], v[144:147], v[136:139], v[48:63]
	ds_read_b64_tr_b16 v[140:141], v188 offset:52224
	ds_read_b64_tr_b16 v[142:143], v188 offset:52736
	v_exp_f32_e32 v124, v124
	v_exp_f32_e32 v125, v125
	v_mfma_f32_32x32x16_bf16 v[32:47], v[144:147], v[72:75], v[32:47]
	ds_read_b64_tr_b16 v[136:137], v188 offset:56320
	ds_read_b64_tr_b16 v[138:139], v188 offset:56832
	v_exp_f32_e32 v126, v126
	v_exp_f32_e32 v127, v127
	s_waitcnt lgkmcnt(14)
	v_mfma_f32_32x32x16_bf16 v[16:31], v[156:159], v[76:79], v[16:31]
	v_exp_f32_e32 v96, v96
	v_exp_f32_e32 v97, v97
	v_mfma_f32_32x32x16_bf16 v[0:15], v[156:159], v[128:131], v[0:15]
	v_exp_f32_e32 v98, v98
	v_exp_f32_e32 v99, v99
	v_mfma_f32_32x32x16_bf16 v[16:31], v[152:155], v[132:135], v[16:31]
	v_exp_f32_e32 v100, v100
	v_exp_f32_e32 v101, v101
	s_waitcnt lgkmcnt(12)
	v_mfma_f32_32x32x16_bf16 v[0:15], v[152:155], v[178:181], v[0:15]
	v_exp_f32_e32 v102, v102
	v_exp_f32_e32 v103, v103
	s_waitcnt lgkmcnt(8)
	v_mfma_f32_32x32x16_bf16 v[16:31], v[148:151], v[190:193], v[16:31]
	v_exp_f32_e32 v104, v104
	v_exp_f32_e32 v105, v105
	s_waitcnt lgkmcnt(4)
	v_mfma_f32_32x32x16_bf16 v[0:15], v[148:151], v[194:197], v[0:15]
	v_exp_f32_e32 v106, v106
	v_exp_f32_e32 v107, v107
	s_waitcnt lgkmcnt(2)
	v_mfma_f32_32x32x16_bf16 v[16:31], v[144:147], v[140:143], v[16:31]
	v_exp_f32_e32 v108, v108
	v_exp_f32_e32 v109, v109
	s_waitcnt lgkmcnt(0)
	v_mfma_f32_32x32x16_bf16 v[0:15], v[144:147], v[136:139], v[0:15]
	v_exp_f32_e32 v110, v110
	v_exp_f32_e32 v111, v111
	s_waitcnt vmcnt(3) lgkmcnt(0)
	s_barrier
	ds_read_b64_tr_b16 v[178:179], v188 offset:57344
	ds_read_b64_tr_b16 v[180:181], v188 offset:57856
	v_add_f32_e32 v76, v112, v113
	ds_read_b128 v[72:75], v168
	v_add_f32_e32 v76, v114, v76
	v_add_f32_e32 v76, v115, v76
	v_add_f32_e32 v76, v116, v76
	v_add_f32_e32 v76, v117, v76
	v_cvt_pk_bf16_f32 v156, v112, v113
	v_cvt_pk_bf16_f32 v157, v114, v115
	s_waitcnt lgkmcnt(0)
	v_mfma_f32_32x32x16_bf16 v[128:143], v[68:71], v[72:75], 0
	ds_read_b64_tr_b16 v[112:113], v188 offset:61440
	ds_read_b64_tr_b16 v[114:115], v188 offset:61952
	ds_read_b128 v[68:71], v168
	v_add_f32_e32 v72, v118, v76
	v_add_f32_e32 v72, v119, v72
	v_add_f32_e32 v72, v120, v72
	v_add_f32_e32 v144, v121, v72
	s_waitcnt lgkmcnt(0)
	v_mfma_f32_32x32x16_bf16 v[64:79], v[64:67], v[68:71], 0
	v_cvt_pk_bf16_f32 v158, v116, v117
	v_cvt_pk_bf16_f32 v159, v118, v119
	ds_read_b64_tr_b16 v[116:117], v188 offset:58368
	ds_read_b64_tr_b16 v[118:119], v188 offset:58880
	ds_read_b128 v[190:193], v168 offset:1024
	v_add_f32_e32 v144, v122, v144
	v_add_f32_e32 v144, v123, v144
	v_add_f32_e32 v144, v124, v144
	v_add_f32_e32 v144, v125, v144
	v_cvt_pk_bf16_f32 v152, v120, v121
	v_cvt_pk_bf16_f32 v153, v122, v123
	s_waitcnt lgkmcnt(0)
	v_mfma_f32_32x32x16_bf16 v[128:143], v[164:167], v[190:193], v[128:143]
	ds_read_b64_tr_b16 v[120:121], v188 offset:62464
	ds_read_b64_tr_b16 v[122:123], v188 offset:62976
	ds_read_b128 v[164:167], v168 offset:1024
	v_add_f32_e32 v144, v126, v144
	v_add_f32_e32 v144, v127, v144
	v_add_f32_e32 v144, v96, v144
	v_add_f32_e32 v144, v97, v144
	s_waitcnt lgkmcnt(0)
	v_mfma_f32_32x32x16_bf16 v[64:79], v[92:95], v[164:167], v[64:79]
	v_cvt_pk_bf16_f32 v154, v124, v125
	v_cvt_pk_bf16_f32 v155, v126, v127
	ds_read_b64_tr_b16 v[92:93], v188 offset:59392
	ds_read_b64_tr_b16 v[94:95], v188 offset:59904
	ds_read_b128 v[124:127], v168 offset:2048
	v_add_f32_e32 v144, v98, v144
	v_add_f32_e32 v144, v99, v144
	v_add_f32_e32 v144, v100, v144
	v_add_f32_e32 v144, v101, v144
	v_cvt_pk_bf16_f32 v148, v96, v97
	v_cvt_pk_bf16_f32 v149, v98, v99
	s_waitcnt lgkmcnt(0)
; #define WAIT_BAR(N) asm volatile("s_waitcnt vmcnt(" #N ") lgkmcnt(0)\n\ts_barrier":::"memory")
;   #define RESC() do{ if(!NOMAX&&resc){ asm volatile("s_waitcnt lgkmcnt(0)":::"memory"); \
;       _Pragma("unroll") for(int d_=0;d_<2*VM;++d_) _Pragma("unroll") for(int r=0;r<16;++r)o[d_][r]*=wsf[crow(r,hi)]; } }while(0)
;   #define ROT() do{sl_prev=sl_cur;sl_cur=sl_next;sl_next=(sl_next==(NSLOT-1)*SLOTB)?0:sl_next+SLOTB;}while(0)
; template<int THRL,int VM,bool NOMAX> __device__ __forceinline__ void attn_unit(const bf16*Qb,const bf16*__restrict__ Kh,const bf16*__restrict__ Vh,bf16*Ob,const int NT,const int sp,float*wscr,char*shm){
;     ...
;   int t=1;
;   for(;t+5<NT;t+=2){
;     STEP(pB0,pB1,pA0,pA1,t,true,true,true);     if constexpr(VM==2){WAIT_BAR(3);}else{WAIT_BAR(2);} RESC(); ROT();
;     STEP(pA0,pA1,pB0,pB1,t+1,true,true,true);   if constexpr(VM==2){WAIT_BAR(3);}else{WAIT_BAR(2);} RESC(); ROT();
	v_mfma_f32_32x32x16_bf16 v[128:143], v[160:163], v[124:127], v[128:143]
	ds_read_b64_tr_b16 v[96:97], v188 offset:63488
	ds_read_b64_tr_b16 v[98:99], v188 offset:64000
	ds_read_b128 v[124:127], v168 offset:2048
	v_add_f32_e32 v144, v102, v144
	v_add_f32_e32 v144, v103, v144
	v_add_f32_e32 v144, v104, v144
	v_add_f32_e32 v144, v105, v144
	s_waitcnt lgkmcnt(0)
	v_mfma_f32_32x32x16_bf16 v[64:79], v[84:87], v[124:127], v[64:79]
	v_cvt_pk_bf16_f32 v150, v100, v101
	v_cvt_pk_bf16_f32 v151, v102, v103
	ds_read_b64_tr_b16 v[100:101], v188 offset:60416
	ds_read_b64_tr_b16 v[102:103], v188 offset:60928
	ds_read_b128 v[84:87], v168 offset:3072
	v_add_f32_e32 v124, v106, v144
	v_add_f32_e32 v124, v107, v124
	v_add_f32_e32 v124, v108, v124
	v_add_f32_e32 v124, v109, v124
	v_cvt_pk_bf16_f32 v144, v104, v105
	v_cvt_pk_bf16_f32 v145, v106, v107
	s_waitcnt lgkmcnt(0)
	v_mfma_f32_32x32x16_bf16 v[128:143], v[88:91], v[84:87], v[128:143]
	ds_read_b64_tr_b16 v[88:89], v188 offset:64512
	ds_read_b64_tr_b16 v[90:91], v188 offset:65024
	ds_read_b128 v[84:87], v168 offset:3072
	v_add_f32_e32 v104, v110, v124
	v_add_f32_e32 v104, v111, v104
	v_add_f32_e32 v104, 0, v104
	v_cvt_pk_bf16_f32 v146, v108, v109
	s_waitcnt lgkmcnt(0)
	v_mfma_f32_32x32x16_bf16 v[64:79], v[80:83], v[84:87], v[64:79]
	v_cvt_pk_bf16_f32 v147, v110, v111
	v_lshl_add_u64 v[80:81], v[174:175], 0, s[64:65]
	s_mov_b32 s86, m0
	s_mov_b32 m0, s17
	s_nop 0
	global_load_lds_dwordx4 v[80:81], off
	s_mov_b32 m0, s86
	v_lshl_add_u64 v[80:81], v[170:171], 0, s[66:67]
	s_add_i32 s17, s85, 0xa000
	s_mov_b32 s86, m0
	s_mov_b32 m0, s17
	s_nop 0
	global_load_lds_dwordx4 v[80:81], off
	s_mov_b32 m0, s86
	v_lshl_add_u64 v[80:81], v[172:173], 0, s[66:67]
	s_add_i32 s17, s85, 0xc000
	s_mov_b32 s86, m0
	s_mov_b32 m0, s17
	s_nop 0
	global_load_lds_dwordx4 v[80:81], off
	s_mov_b32 m0, s86
	v_add_f32_e32 v198, v198, v104
	v_mfma_f32_32x32x16_bf16 v[48:63], v[156:159], v[178:181], v[48:63]
	ds_read_b64_tr_b16 v[104:105], v177 offset:40960
	ds_read_b64_tr_b16 v[106:107], v177 offset:41472
	v_exp_f32_e32 v128, v128
	v_exp_f32_e32 v129, v129
	v_mfma_f32_32x32x16_bf16 v[32:47], v[156:159], v[112:115], v[32:47]
	ds_read_b64_tr_b16 v[108:109], v177 offset:45056
	ds_read_b64_tr_b16 v[110:111], v177 offset:45568
	v_exp_f32_e32 v130, v130
	v_exp_f32_e32 v131, v131
	ds_read_b128 v[84:87], v234 offset:8192
	ds_read_b128 v[80:83], v234 offset:12288
	v_mfma_f32_32x32x16_bf16 v[48:63], v[152:155], v[116:119], v[48:63]
	ds_read_b64_tr_b16 v[178:179], v177 offset:41984
	ds_read_b64_tr_b16 v[180:181], v177 offset:42496
	v_exp_f32_e32 v132, v132
	v_exp_f32_e32 v133, v133
	ds_read_b128 v[164:167], v235 offset:8192
	ds_read_b128 v[124:127], v235 offset:12288
	v_mfma_f32_32x32x16_bf16 v[32:47], v[152:155], v[120:123], v[32:47]
	ds_read_b64_tr_b16 v[190:191], v177 offset:46080
	ds_read_b64_tr_b16 v[192:193], v177 offset:46592
	v_exp_f32_e32 v134, v134
	v_exp_f32_e32 v135, v135
	ds_read_b128 v[160:163], v236 offset:8192
	ds_read_b128 v[116:119], v236 offset:12288
	v_mfma_f32_32x32x16_bf16 v[48:63], v[148:151], v[92:95], v[48:63]
	ds_read_b64_tr_b16 v[194:195], v177 offset:43008
	ds_read_b64_tr_b16 v[196:197], v177 offset:43520
	v_exp_f32_e32 v136, v136
	v_exp_f32_e32 v137, v137
	ds_read_b128 v[120:123], v237 offset:8192
	ds_read_b128 v[112:115], v237 offset:12288
	v_mfma_f32_32x32x16_bf16 v[32:47], v[148:151], v[96:99], v[32:47]
	ds_read_b64_tr_b16 v[92:93], v177 offset:47104
	ds_read_b64_tr_b16 v[94:95], v177 offset:47616
	v_exp_f32_e32 v138, v138
	v_exp_f32_e32 v139, v139
	v_mfma_f32_32x32x16_bf16 v[48:63], v[144:147], v[100:103], v[48:63]
	ds_read_b64_tr_b16 v[96:97], v177 offset:44032
	ds_read_b64_tr_b16 v[98:99], v177 offset:44544
	v_exp_f32_e32 v140, v140
	v_exp_f32_e32 v141, v141
	v_mfma_f32_32x32x16_bf16 v[32:47], v[144:147], v[88:91], v[32:47]
	ds_read_b64_tr_b16 v[100:101], v177 offset:48128
	ds_read_b64_tr_b16 v[102:103], v177 offset:48640
	v_exp_f32_e32 v142, v142
	v_exp_f32_e32 v143, v143
	s_waitcnt lgkmcnt(14)
	v_mfma_f32_32x32x16_bf16 v[16:31], v[156:159], v[104:107], v[16:31]
	v_exp_f32_e32 v64, v64
	v_exp_f32_e32 v65, v65
	v_mfma_f32_32x32x16_bf16 v[0:15], v[156:159], v[108:111], v[0:15]
	v_exp_f32_e32 v66, v66
	v_exp_f32_e32 v67, v67
	v_mfma_f32_32x32x16_bf16 v[16:31], v[152:155], v[178:181], v[16:31]
	v_exp_f32_e32 v68, v68
	v_exp_f32_e32 v69, v69
	s_waitcnt lgkmcnt(12)
	v_mfma_f32_32x32x16_bf16 v[0:15], v[152:155], v[190:193], v[0:15]
	v_exp_f32_e32 v70, v70
	v_exp_f32_e32 v71, v71
	s_waitcnt lgkmcnt(8)
	v_mfma_f32_32x32x16_bf16 v[16:31], v[148:151], v[194:197], v[16:31]
	v_exp_f32_e32 v72, v72
	v_exp_f32_e32 v73, v73
	s_waitcnt lgkmcnt(4)
	v_mfma_f32_32x32x16_bf16 v[0:15], v[148:151], v[92:95], v[0:15]
	v_exp_f32_e32 v74, v74
	v_exp_f32_e32 v75, v75
	s_waitcnt lgkmcnt(2)
	v_mfma_f32_32x32x16_bf16 v[16:31], v[144:147], v[96:99], v[16:31]
	v_exp_f32_e32 v76, v76
	v_exp_f32_e32 v77, v77
	s_waitcnt lgkmcnt(0)
	v_mfma_f32_32x32x16_bf16 v[0:15], v[144:147], v[100:103], v[0:15]
	v_exp_f32_e32 v78, v78
	v_exp_f32_e32 v79, v79
	s_waitcnt vmcnt(3) lgkmcnt(0)
	s_barrier
; #define WAIT_BAR(N) asm volatile("s_waitcnt vmcnt(" #N ") lgkmcnt(0)\n\ts_barrier":::"memory")
;   #define RESC() do{ if(!NOMAX&&resc){ asm volatile("s_waitcnt lgkmcnt(0)":::"memory"); \
;       _Pragma("unroll") for(int d_=0;d_<2*VM;++d_) _Pragma("unroll") for(int r=0;r<16;++r)o[d_][r]*=wsf[crow(r,hi)]; } }while(0)
;   #define ROT() do{sl_prev=sl_cur;sl_cur=sl_next;sl_next=(sl_next==(NSLOT-1)*SLOTB)?0:sl_next+SLOTB;}while(0)
;   #define ENDW(tt) do{ if((tt)+3<NT){ if constexpr(VM==2){WAIT_BAR(3);}else{WAIT_BAR(2);} } else if((tt)+2<NT){ if constexpr(VM==2){WAIT_BAR(2);}else{WAIT_BAR(1);} } else {WAIT_BAR(0);} }while(0)
; template<int THRL,int VM,bool NOMAX> __device__ __forceinline__ void attn_unit(const bf16*Qb,const bf16*__restrict__ Kh,const bf16*__restrict__ Vh,bf16*Ob,const int NT,const int sp,float*wscr,char*shm){
;     ...
;   int t=1;
;   for(;t+5<NT;t+=2){
;     STEP(pB0,pB1,pA0,pA1,t,true,true,true);     if constexpr(VM==2){WAIT_BAR(3);}else{WAIT_BAR(2);} RESC(); ROT();
;     STEP(pA0,pA1,pB0,pB1,t+1,true,true,true);   if constexpr(VM==2){WAIT_BAR(3);}else{WAIT_BAR(2);} RESC(); ROT();
;   }
;     ...
;   for(;t+1<NT;t+=2){
;     STEP(pB0,pB1,pA0,pA1,t,(t+3<NT),(t+1<NT),(t+1<NT));       ENDW(t);   RESC(); ROT();
;     STEP(pA0,pA1,pB0,pB1,t+1,(t+4<NT),(t+2<NT),(t+2<NT));     ENDW(t+1); RESC(); ROT();
	ds_read_b64_tr_b16 v[178:179], v188 offset:24576
	ds_read_b64_tr_b16 v[180:181], v188 offset:25088
	v_add_f32_e32 v92, v128, v129
	ds_read_b128 v[88:91], v168
	v_add_f32_e32 v92, v130, v92
	v_add_f32_e32 v92, v131, v92
	v_add_f32_e32 v92, v132, v92
	v_add_f32_e32 v92, v133, v92
	v_cvt_pk_bf16_f32 v156, v128, v129
	v_cvt_pk_bf16_f32 v157, v130, v131
	s_waitcnt lgkmcnt(0)
	v_mfma_f32_32x32x16_bf16 v[96:111], v[84:87], v[88:91], 0
	ds_read_b64_tr_b16 v[128:129], v188 offset:28672
	ds_read_b64_tr_b16 v[130:131], v188 offset:29184
	ds_read_b128 v[84:87], v168
	v_add_f32_e32 v88, v134, v92
	v_add_f32_e32 v88, v135, v88
	v_add_f32_e32 v88, v136, v88
	v_add_f32_e32 v144, v137, v88
	v_cvt_pk_bf16_f32 v158, v132, v133
	v_cvt_pk_bf16_f32 v159, v134, v135
	s_waitcnt lgkmcnt(0)
	v_mfma_f32_32x32x16_bf16 v[80:95], v[80:83], v[84:87], 0
	ds_read_b64_tr_b16 v[132:133], v188 offset:25600
	ds_read_b64_tr_b16 v[134:135], v188 offset:26112
	ds_read_b128 v[190:193], v168 offset:1024
	v_add_f32_e32 v144, v138, v144
	v_add_f32_e32 v144, v139, v144
	v_add_f32_e32 v144, v140, v144
	v_add_f32_e32 v144, v141, v144
	v_cvt_pk_bf16_f32 v152, v136, v137
	v_cvt_pk_bf16_f32 v153, v138, v139
	s_waitcnt lgkmcnt(0)
	v_mfma_f32_32x32x16_bf16 v[96:111], v[164:167], v[190:193], v[96:111]
	ds_read_b64_tr_b16 v[136:137], v188 offset:29696
	ds_read_b64_tr_b16 v[138:139], v188 offset:30208
	ds_read_b128 v[164:167], v168 offset:1024
	v_add_f32_e32 v144, v142, v144
	v_add_f32_e32 v144, v143, v144
	v_add_f32_e32 v144, v64, v144
	v_add_f32_e32 v144, v65, v144
	v_cvt_pk_bf16_f32 v154, v140, v141
	v_cvt_pk_bf16_f32 v155, v142, v143
	s_waitcnt lgkmcnt(0)
	v_mfma_f32_32x32x16_bf16 v[80:95], v[124:127], v[164:167], v[80:95]
	ds_read_b64_tr_b16 v[124:125], v188 offset:26624
	ds_read_b64_tr_b16 v[126:127], v188 offset:27136
	ds_read_b128 v[140:143], v168 offset:2048
	v_add_f32_e32 v144, v66, v144
	v_add_f32_e32 v144, v67, v144
	v_add_f32_e32 v144, v68, v144
	v_add_f32_e32 v144, v69, v144
	v_cvt_pk_bf16_f32 v148, v64, v65
	v_cvt_pk_bf16_f32 v149, v66, v67
	s_waitcnt lgkmcnt(0)
	v_mfma_f32_32x32x16_bf16 v[96:111], v[160:163], v[140:143], v[96:111]
	ds_read_b64_tr_b16 v[190:191], v188 offset:30720
	ds_read_b64_tr_b16 v[192:193], v188 offset:31232
	ds_read_b128 v[64:67], v168 offset:2048
	v_add_f32_e32 v140, v70, v144
	v_add_f32_e32 v140, v71, v140
	v_add_f32_e32 v140, v72, v140
	v_add_f32_e32 v140, v73, v140
	v_cvt_pk_bf16_f32 v150, v68, v69
	v_cvt_pk_bf16_f32 v151, v70, v71
	s_waitcnt lgkmcnt(0)
	v_mfma_f32_32x32x16_bf16 v[80:95], v[116:119], v[64:67], v[80:95]
	ds_read_b64_tr_b16 v[116:117], v188 offset:27648
	ds_read_b64_tr_b16 v[118:119], v188 offset:28160
	ds_read_b128 v[64:67], v168 offset:3072
	v_add_f32_e32 v68, v74, v140
	v_add_f32_e32 v68, v75, v68
	v_add_f32_e32 v68, v76, v68
	v_add_f32_e32 v68, v77, v68
	v_cvt_pk_bf16_f32 v144, v72, v73
	v_cvt_pk_bf16_f32 v145, v74, v75
	s_waitcnt lgkmcnt(0)
	v_mfma_f32_32x32x16_bf16 v[96:111], v[120:123], v[64:67], v[96:111]
	ds_read_b64_tr_b16 v[72:73], v188 offset:31744
	ds_read_b64_tr_b16 v[74:75], v188 offset:32256
	ds_read_b128 v[64:67], v168 offset:3072
	v_add_f32_e32 v68, v78, v68
	v_add_f32_e32 v68, v79, v68
	v_add_f32_e32 v68, 0, v68
	v_cvt_pk_bf16_f32 v146, v76, v77
	v_cvt_pk_bf16_f32 v147, v78, v79
	s_waitcnt lgkmcnt(0)
	v_mfma_f32_32x32x16_bf16 v[80:95], v[112:115], v[64:67], v[80:95]
	v_lshl_add_u64 v[64:65], v[170:171], 0, s[60:61]
	s_add_i32 s17, s85, 0xe000
	s_mov_b32 s86, m0
	s_mov_b32 m0, s17
	s_nop 0
	global_load_lds_dwordx4 v[64:65], off
	s_mov_b32 m0, s86
	v_lshl_add_u64 v[64:65], v[172:173], 0, s[60:61]
	s_add_i32 s85, s85, 0x10000
	s_mov_b32 s17, m0
	s_mov_b32 m0, s85
	s_nop 0
	global_load_lds_dwordx4 v[64:65], off
	s_mov_b32 m0, s17
	v_add_f32_e32 v174, v198, v68
	v_mfma_f32_32x32x16_bf16 v[48:63], v[156:159], v[178:181], v[48:63]
	ds_read_b64_tr_b16 v[76:77], v188 offset:32768
	ds_read_b64_tr_b16 v[78:79], v188 offset:33280
	v_exp_f32_e32 v96, v96
	v_exp_f32_e32 v97, v97
	v_mfma_f32_32x32x16_bf16 v[32:47], v[156:159], v[128:131], v[32:47]
	ds_read_b64_tr_b16 v[112:113], v188 offset:36864
	ds_read_b64_tr_b16 v[114:115], v188 offset:37376
	v_exp_f32_e32 v98, v98
	v_exp_f32_e32 v99, v99
	ds_read_b128 v[68:71], v234 offset:16384
	ds_read_b128 v[64:67], v234 offset:20480
	v_mfma_f32_32x32x16_bf16 v[48:63], v[152:155], v[132:135], v[48:63]
	ds_read_b64_tr_b16 v[120:121], v188 offset:33792
	ds_read_b64_tr_b16 v[122:123], v188 offset:34304
	v_exp_f32_e32 v100, v100
	v_exp_f32_e32 v101, v101
	ds_read_b128 v[164:167], v235 offset:16384
	ds_read_b128 v[140:143], v235 offset:20480
	v_mfma_f32_32x32x16_bf16 v[32:47], v[152:155], v[136:139], v[32:47]
	ds_read_b64_tr_b16 v[178:179], v188 offset:37888
	ds_read_b64_tr_b16 v[180:181], v188 offset:38400
	v_exp_f32_e32 v102, v102
	v_exp_f32_e32 v103, v103
	ds_read_b128 v[160:163], v236 offset:16384
	ds_read_b128 v[132:135], v236 offset:20480
	v_mfma_f32_32x32x16_bf16 v[48:63], v[148:151], v[124:127], v[48:63]
	ds_read_b64_tr_b16 v[194:195], v188 offset:34816
	ds_read_b64_tr_b16 v[196:197], v188 offset:35328
	v_exp_f32_e32 v104, v104
	v_exp_f32_e32 v105, v105
	ds_read_b128 v[136:139], v237 offset:16384
	ds_read_b128 v[128:131], v237 offset:20480
	v_mfma_f32_32x32x16_bf16 v[32:47], v[148:151], v[190:193], v[32:47]
	ds_read_b64_tr_b16 v[124:125], v188 offset:38912
	ds_read_b64_tr_b16 v[126:127], v188 offset:39424
	v_exp_f32_e32 v106, v106
	v_exp_f32_e32 v107, v107
	v_mfma_f32_32x32x16_bf16 v[48:63], v[144:147], v[116:119], v[48:63]
	ds_read_b64_tr_b16 v[190:191], v188 offset:35840
	ds_read_b64_tr_b16 v[192:193], v188 offset:36352
	v_exp_f32_e32 v108, v108
	v_exp_f32_e32 v109, v109
	v_mfma_f32_32x32x16_bf16 v[32:47], v[144:147], v[72:75], v[32:47]
	ds_read_b64_tr_b16 v[116:117], v188 offset:39936
	ds_read_b64_tr_b16 v[118:119], v188 offset:40448
	v_exp_f32_e32 v110, v110
	v_exp_f32_e32 v111, v111
	s_waitcnt lgkmcnt(14)
	v_mfma_f32_32x32x16_bf16 v[16:31], v[156:159], v[76:79], v[16:31]
	v_exp_f32_e32 v80, v80
	v_exp_f32_e32 v81, v81
	v_mfma_f32_32x32x16_bf16 v[0:15], v[156:159], v[112:115], v[0:15]
	v_exp_f32_e32 v82, v82
	v_exp_f32_e32 v83, v83
	v_mfma_f32_32x32x16_bf16 v[16:31], v[152:155], v[120:123], v[16:31]
	v_exp_f32_e32 v84, v84
	v_exp_f32_e32 v85, v85
	s_waitcnt lgkmcnt(12)
	v_mfma_f32_32x32x16_bf16 v[0:15], v[152:155], v[178:181], v[0:15]
	v_exp_f32_e32 v86, v86
	v_exp_f32_e32 v87, v87
	s_waitcnt lgkmcnt(8)
	v_mfma_f32_32x32x16_bf16 v[16:31], v[148:151], v[194:197], v[16:31]
	v_exp_f32_e32 v88, v88
	v_exp_f32_e32 v89, v89
	s_waitcnt lgkmcnt(4)
	v_mfma_f32_32x32x16_bf16 v[0:15], v[148:151], v[124:127], v[0:15]
	v_exp_f32_e32 v90, v90
	v_exp_f32_e32 v91, v91
	s_waitcnt lgkmcnt(2)
	v_mfma_f32_32x32x16_bf16 v[16:31], v[144:147], v[190:193], v[16:31]
	v_exp_f32_e32 v92, v92
	v_exp_f32_e32 v93, v93
	s_waitcnt lgkmcnt(0)
	v_mfma_f32_32x32x16_bf16 v[0:15], v[144:147], v[116:119], v[0:15]
	v_exp_f32_e32 v94, v94
	v_exp_f32_e32 v95, v95
	s_waitcnt vmcnt(2) lgkmcnt(0)
	s_barrier
; #define WAIT_BAR(N) asm volatile("s_waitcnt vmcnt(" #N ") lgkmcnt(0)\n\ts_barrier":::"memory")
;   #define RESC() do{ if(!NOMAX&&resc){ asm volatile("s_waitcnt lgkmcnt(0)":::"memory"); \
;       _Pragma("unroll") for(int d_=0;d_<2*VM;++d_) _Pragma("unroll") for(int r=0;r<16;++r)o[d_][r]*=wsf[crow(r,hi)]; } }while(0)
;   #define ROT() do{sl_prev=sl_cur;sl_cur=sl_next;sl_next=(sl_next==(NSLOT-1)*SLOTB)?0:sl_next+SLOTB;}while(0)
;   #define ENDW(tt) do{ if((tt)+3<NT){ if constexpr(VM==2){WAIT_BAR(3);}else{WAIT_BAR(2);} } else if((tt)+2<NT){ if constexpr(VM==2){WAIT_BAR(2);}else{WAIT_BAR(1);} } else {WAIT_BAR(0);} }while(0)
; template<int THRL,int VM,bool NOMAX> __device__ __forceinline__ void attn_unit(const bf16*Qb,const bf16*__restrict__ Kh,const bf16*__restrict__ Vh,bf16*Ob,const int NT,const int sp,float*wscr,char*shm){
;     ...
;   int t=1;
;   for(;t+5<NT;t+=2){
;     STEP(pB0,pB1,pA0,pA1,t,true,true,true);     if constexpr(VM==2){WAIT_BAR(3);}else{WAIT_BAR(2);} RESC(); ROT();
;     STEP(pA0,pA1,pB0,pB1,t+1,true,true,true);   if constexpr(VM==2){WAIT_BAR(3);}else{WAIT_BAR(2);} RESC(); ROT();
;   }
;     ...
;   for(;t+1<NT;t+=2){
;     STEP(pB0,pB1,pA0,pA1,t,(t+3<NT),(t+1<NT),(t+1<NT));       ENDW(t);   RESC(); ROT();
;     STEP(pA0,pA1,pB0,pB1,t+1,(t+4<NT),(t+2<NT),(t+2<NT));     ENDW(t+1); RESC(); ROT();
	ds_read_b64_tr_b16 v[178:179], v188 offset:40960
	ds_read_b64_tr_b16 v[180:181], v188 offset:41472
	v_add_f32_e32 v76, v96, v97
	ds_read_b128 v[72:75], v168
	v_add_f32_e32 v76, v98, v76
	v_add_f32_e32 v76, v99, v76
	v_add_f32_e32 v76, v100, v76
	v_add_f32_e32 v76, v101, v76
	v_cvt_pk_bf16_f32 v156, v96, v97
	v_cvt_pk_bf16_f32 v157, v98, v99
	s_waitcnt lgkmcnt(0)
	v_mfma_f32_32x32x16_bf16 v[112:127], v[68:71], v[72:75], 0
	ds_read_b64_tr_b16 v[96:97], v188 offset:45056
	ds_read_b64_tr_b16 v[98:99], v188 offset:45568
	ds_read_b128 v[68:71], v168
	v_add_f32_e32 v72, v102, v76
	v_add_f32_e32 v72, v103, v72
	v_add_f32_e32 v72, v104, v72
	v_add_f32_e32 v144, v105, v72
	s_waitcnt lgkmcnt(0)
	v_mfma_f32_32x32x16_bf16 v[64:79], v[64:67], v[68:71], 0
	v_cvt_pk_bf16_f32 v158, v100, v101
	v_cvt_pk_bf16_f32 v159, v102, v103
	ds_read_b64_tr_b16 v[100:101], v188 offset:41984
	ds_read_b64_tr_b16 v[102:103], v188 offset:42496
	ds_read_b128 v[190:193], v168 offset:1024
	v_add_f32_e32 v144, v106, v144
	v_add_f32_e32 v144, v107, v144
	v_add_f32_e32 v144, v108, v144
	v_add_f32_e32 v144, v109, v144
	v_cvt_pk_bf16_f32 v152, v104, v105
	v_cvt_pk_bf16_f32 v153, v106, v107
	s_waitcnt lgkmcnt(0)
	v_mfma_f32_32x32x16_bf16 v[112:127], v[164:167], v[190:193], v[112:127]
	ds_read_b64_tr_b16 v[104:105], v188 offset:46080
	ds_read_b64_tr_b16 v[106:107], v188 offset:46592
	ds_read_b128 v[164:167], v168 offset:1024
	v_add_f32_e32 v144, v110, v144
	v_add_f32_e32 v144, v111, v144
	v_add_f32_e32 v144, v80, v144
	v_add_f32_e32 v144, v81, v144
	s_waitcnt lgkmcnt(0)
	v_mfma_f32_32x32x16_bf16 v[64:79], v[140:143], v[164:167], v[64:79]
	v_cvt_pk_bf16_f32 v154, v108, v109
	v_cvt_pk_bf16_f32 v155, v110, v111
	ds_read_b64_tr_b16 v[108:109], v188 offset:43008
	ds_read_b64_tr_b16 v[110:111], v188 offset:43520
	ds_read_b128 v[140:143], v168 offset:2048
	v_add_f32_e32 v144, v82, v144
	v_add_f32_e32 v144, v83, v144
	v_add_f32_e32 v144, v84, v144
	v_add_f32_e32 v144, v85, v144
	v_cvt_pk_bf16_f32 v148, v80, v81
	v_cvt_pk_bf16_f32 v149, v82, v83
	s_waitcnt lgkmcnt(0)
	v_mfma_f32_32x32x16_bf16 v[112:127], v[160:163], v[140:143], v[112:127]
	ds_read_b64_tr_b16 v[190:191], v188 offset:47104
	ds_read_b64_tr_b16 v[192:193], v188 offset:47616
	ds_read_b128 v[80:83], v168 offset:2048
	v_add_f32_e32 v140, v86, v144
	v_add_f32_e32 v140, v87, v140
	v_add_f32_e32 v140, v88, v140
	v_add_f32_e32 v140, v89, v140
	s_waitcnt lgkmcnt(0)
	v_mfma_f32_32x32x16_bf16 v[64:79], v[132:135], v[80:83], v[64:79]
	v_cvt_pk_bf16_f32 v150, v84, v85
	v_cvt_pk_bf16_f32 v151, v86, v87
	ds_read_b64_tr_b16 v[84:85], v188 offset:44032
	ds_read_b64_tr_b16 v[86:87], v188 offset:44544
	ds_read_b128 v[80:83], v168 offset:3072
	v_add_f32_e32 v132, v90, v140
	v_add_f32_e32 v132, v91, v132
	v_add_f32_e32 v132, v92, v132
	v_add_f32_e32 v132, v93, v132
	v_cvt_pk_bf16_f32 v144, v88, v89
	v_cvt_pk_bf16_f32 v145, v90, v91
	s_waitcnt lgkmcnt(0)
	v_mfma_f32_32x32x16_bf16 v[112:127], v[136:139], v[80:83], v[112:127]
	ds_read_b64_tr_b16 v[88:89], v188 offset:48128
	ds_read_b64_tr_b16 v[90:91], v188 offset:48640
	ds_read_b128 v[80:83], v168 offset:3072
	v_add_f32_e32 v132, v94, v132
	v_add_f32_e32 v132, v95, v132
	v_add_f32_e32 v132, 0, v132
	v_cvt_pk_bf16_f32 v146, v92, v93
	s_waitcnt lgkmcnt(0)
	v_mfma_f32_32x32x16_bf16 v[64:79], v[128:131], v[80:83], v[64:79]
	v_cvt_pk_bf16_f32 v147, v94, v95
	v_lshl_add_u64 v[80:81], v[170:171], 0, s[64:65]
	s_mov_b32 s17, m0
	s_mov_b32 m0, s16
	s_nop 0
	global_load_lds_dwordx4 v[80:81], off
	s_mov_b32 m0, s17
	v_lshl_add_u64 v[80:81], v[172:173], 0, s[64:65]
	s_mov_b32 s16, m0
	s_mov_b32 m0, s35
	s_nop 0
	global_load_lds_dwordx4 v[80:81], off
	s_mov_b32 m0, s16
	v_add_f32_e32 v174, v174, v132
	v_mfma_f32_32x32x16_bf16 v[48:63], v[156:159], v[178:181], v[48:63]
	ds_read_b64_tr_b16 v[92:93], v188 offset:49152
	ds_read_b64_tr_b16 v[94:95], v188 offset:49664
	v_exp_f32_e32 v112, v112
	v_exp_f32_e32 v113, v113
	v_mfma_f32_32x32x16_bf16 v[32:47], v[156:159], v[96:99], v[32:47]
	ds_read_b64_tr_b16 v[170:171], v188 offset:53248
	ds_read_b64_tr_b16 v[172:173], v188 offset:53760
	v_exp_f32_e32 v114, v114
	v_exp_f32_e32 v115, v115
	ds_read_b128 v[80:83], v234
	ds_read_b128 v[96:99], v234 offset:4096
	v_mfma_f32_32x32x16_bf16 v[48:63], v[152:155], v[100:103], v[48:63]
	ds_read_b64_tr_b16 v[178:179], v188 offset:50176
	ds_read_b64_tr_b16 v[180:181], v188 offset:50688
	v_exp_f32_e32 v116, v116
	v_exp_f32_e32 v117, v117
	ds_read_b128 v[164:167], v235
	ds_read_b128 v[140:143], v235 offset:4096
	v_mfma_f32_32x32x16_bf16 v[32:47], v[152:155], v[104:107], v[32:47]
	ds_read_b64_tr_b16 v[100:101], v188 offset:54272
	ds_read_b64_tr_b16 v[102:103], v188 offset:54784
	v_exp_f32_e32 v118, v118
	v_exp_f32_e32 v119, v119
	ds_read_b128 v[160:163], v236
	ds_read_b128 v[132:135], v236 offset:4096
	v_mfma_f32_32x32x16_bf16 v[48:63], v[148:151], v[108:111], v[48:63]
	ds_read_b64_tr_b16 v[104:105], v188 offset:51200
	ds_read_b64_tr_b16 v[106:107], v188 offset:51712
	v_exp_f32_e32 v120, v120
	v_exp_f32_e32 v121, v121
	ds_read_b128 v[136:139], v237
	ds_read_b128 v[128:131], v237 offset:4096
	v_mfma_f32_32x32x16_bf16 v[32:47], v[148:151], v[190:193], v[32:47]
	ds_read_b64_tr_b16 v[108:109], v188 offset:55296
	ds_read_b64_tr_b16 v[110:111], v188 offset:55808
	v_exp_f32_e32 v122, v122
	v_exp_f32_e32 v123, v123
	v_mfma_f32_32x32x16_bf16 v[48:63], v[144:147], v[84:87], v[48:63]
	ds_read_b64_tr_b16 v[190:191], v188 offset:52224
	ds_read_b64_tr_b16 v[192:193], v188 offset:52736
	v_exp_f32_e32 v124, v124
	v_exp_f32_e32 v125, v125
	v_mfma_f32_32x32x16_bf16 v[32:47], v[144:147], v[88:91], v[32:47]
	ds_read_b64_tr_b16 v[84:85], v188 offset:56320
	ds_read_b64_tr_b16 v[86:87], v188 offset:56832
	v_exp_f32_e32 v126, v126
	v_exp_f32_e32 v127, v127
	s_waitcnt lgkmcnt(14)
	v_mfma_f32_32x32x16_bf16 v[16:31], v[156:159], v[92:95], v[16:31]
	v_exp_f32_e32 v64, v64
	v_exp_f32_e32 v65, v65
	v_mfma_f32_32x32x16_bf16 v[0:15], v[156:159], v[170:173], v[0:15]
	v_exp_f32_e32 v66, v66
	v_exp_f32_e32 v67, v67
	v_mfma_f32_32x32x16_bf16 v[16:31], v[152:155], v[178:181], v[16:31]
	v_exp_f32_e32 v68, v68
	v_exp_f32_e32 v69, v69
	s_waitcnt lgkmcnt(12)
	v_mfma_f32_32x32x16_bf16 v[0:15], v[152:155], v[100:103], v[0:15]
	v_exp_f32_e32 v70, v70
	v_exp_f32_e32 v71, v71
	s_waitcnt lgkmcnt(8)
	v_mfma_f32_32x32x16_bf16 v[16:31], v[148:151], v[104:107], v[16:31]
	v_exp_f32_e32 v72, v72
	v_exp_f32_e32 v73, v73
	s_waitcnt lgkmcnt(4)
	v_mfma_f32_32x32x16_bf16 v[0:15], v[148:151], v[108:111], v[0:15]
	v_exp_f32_e32 v74, v74
	v_exp_f32_e32 v75, v75
	s_waitcnt lgkmcnt(2)
	v_mfma_f32_32x32x16_bf16 v[16:31], v[144:147], v[190:193], v[16:31]
	v_exp_f32_e32 v76, v76
	v_exp_f32_e32 v77, v77
	s_waitcnt lgkmcnt(0)
	v_mfma_f32_32x32x16_bf16 v[0:15], v[144:147], v[84:87], v[0:15]
	v_exp_f32_e32 v78, v78
	v_exp_f32_e32 v79, v79
	s_waitcnt vmcnt(0) lgkmcnt(0)
	s_barrier
; #define WAIT_BAR(N) asm volatile("s_waitcnt vmcnt(" #N ") lgkmcnt(0)\n\ts_barrier":::"memory")
;   #define RESC() do{ if(!NOMAX&&resc){ asm volatile("s_waitcnt lgkmcnt(0)":::"memory"); \
;       _Pragma("unroll") for(int d_=0;d_<2*VM;++d_) _Pragma("unroll") for(int r=0;r<16;++r)o[d_][r]*=wsf[crow(r,hi)]; } }while(0)
;   #define ROT() do{sl_prev=sl_cur;sl_cur=sl_next;sl_next=(sl_next==(NSLOT-1)*SLOTB)?0:sl_next+SLOTB;}while(0)
;   #define ENDW(tt) do{ if((tt)+3<NT){ if constexpr(VM==2){WAIT_BAR(3);}else{WAIT_BAR(2);} } else if((tt)+2<NT){ if constexpr(VM==2){WAIT_BAR(2);}else{WAIT_BAR(1);} } else {WAIT_BAR(0);} }while(0)
; template<int THRL,int VM,bool NOMAX> __device__ __forceinline__ void attn_unit(const bf16*Qb,const bf16*__restrict__ Kh,const bf16*__restrict__ Vh,bf16*Ob,const int NT,const int sp,float*wscr,char*shm){
;     ...
;   int t=1;
;   for(;t+5<NT;t+=2){
;     STEP(pB0,pB1,pA0,pA1,t,true,true,true);     if constexpr(VM==2){WAIT_BAR(3);}else{WAIT_BAR(2);} RESC(); ROT();
;     STEP(pA0,pA1,pB0,pB1,t+1,true,true,true);   if constexpr(VM==2){WAIT_BAR(3);}else{WAIT_BAR(2);} RESC(); ROT();
;   }
;     ...
;   for(;t+1<NT;t+=2){
;     STEP(pB0,pB1,pA0,pA1,t,(t+3<NT),(t+1<NT),(t+1<NT));       ENDW(t);   RESC(); ROT();
;     STEP(pA0,pA1,pB0,pB1,t+1,(t+4<NT),(t+2<NT),(t+2<NT));     ENDW(t+1); RESC(); ROT();
;   }
;   STEP(pB0,pB1,pA0,pA1,NT-1,false,false,false); RESC();
	ds_read_b64_tr_b16 v[170:171], v188 offset:57344
	ds_read_b64_tr_b16 v[172:173], v188 offset:57856
	v_add_f32_e32 v88, v112, v113
	ds_read_b128 v[84:87], v168
	v_add_f32_e32 v88, v114, v88
	v_add_f32_e32 v88, v115, v88
	v_add_f32_e32 v88, v116, v88
	v_add_f32_e32 v104, v117, v88
	v_cvt_pk_bf16_f32 v156, v112, v113
	v_cvt_pk_bf16_f32 v157, v114, v115
	s_waitcnt lgkmcnt(0)
	v_mfma_f32_32x32x16_bf16 v[80:95], v[80:83], v[84:87], 0
	ds_read_b64_tr_b16 v[112:113], v188 offset:61440
	ds_read_b64_tr_b16 v[114:115], v188 offset:61952
	ds_read_b128 v[100:103], v168
	v_add_f32_e32 v104, v118, v104
	v_add_f32_e32 v104, v119, v104
	v_add_f32_e32 v104, v120, v104
	v_add_f32_e32 v144, v121, v104
	v_cvt_pk_bf16_f32 v158, v116, v117
	v_cvt_pk_bf16_f32 v159, v118, v119
	s_waitcnt lgkmcnt(0)
	v_mfma_f32_32x32x16_bf16 v[96:111], v[96:99], v[100:103], 0
	ds_read_b64_tr_b16 v[116:117], v188 offset:58368
	ds_read_b64_tr_b16 v[118:119], v188 offset:58880
	ds_read_b128 v[178:181], v168 offset:1024
	v_add_f32_e32 v144, v122, v144
	v_add_f32_e32 v144, v123, v144
	v_add_f32_e32 v144, v124, v144
	v_add_f32_e32 v144, v125, v144
	v_cvt_pk_bf16_f32 v152, v120, v121
	v_cvt_pk_bf16_f32 v153, v122, v123
	s_waitcnt lgkmcnt(0)
	v_mfma_f32_32x32x16_bf16 v[80:95], v[164:167], v[178:181], v[80:95]
	ds_read_b64_tr_b16 v[120:121], v188 offset:62464
	ds_read_b64_tr_b16 v[122:123], v188 offset:62976
	ds_read_b128 v[164:167], v168 offset:1024
	v_add_f32_e32 v144, v126, v144
	v_add_f32_e32 v144, v127, v144
	v_add_f32_e32 v144, v64, v144
	v_add_f32_e32 v144, v65, v144
	v_cvt_pk_bf16_f32 v154, v124, v125
	v_cvt_pk_bf16_f32 v155, v126, v127
	s_waitcnt lgkmcnt(0)
	v_mfma_f32_32x32x16_bf16 v[96:111], v[140:143], v[164:167], v[96:111]
	ds_read_b64_tr_b16 v[124:125], v188 offset:59392
	ds_read_b64_tr_b16 v[126:127], v188 offset:59904
	ds_read_b128 v[140:143], v168 offset:2048
	v_add_f32_e32 v144, v66, v144
	v_add_f32_e32 v144, v67, v144
	v_add_f32_e32 v144, v68, v144
	v_add_f32_e32 v144, v69, v144
	v_cvt_pk_bf16_f32 v148, v64, v65
	v_cvt_pk_bf16_f32 v149, v66, v67
	s_waitcnt lgkmcnt(0)
	v_mfma_f32_32x32x16_bf16 v[80:95], v[160:163], v[140:143], v[80:95]
	ds_read_b64_tr_b16 v[64:65], v188 offset:63488
	ds_read_b64_tr_b16 v[66:67], v188 offset:64000
	ds_read_b128 v[140:143], v168 offset:2048
	v_add_f32_e32 v144, v70, v144
	v_add_f32_e32 v144, v71, v144
	v_add_f32_e32 v144, v72, v144
	v_add_f32_e32 v144, v73, v144
	v_cvt_pk_bf16_f32 v150, v68, v69
	v_cvt_pk_bf16_f32 v151, v70, v71
	s_waitcnt lgkmcnt(0)
	v_mfma_f32_32x32x16_bf16 v[96:111], v[132:135], v[140:143], v[96:111]
	ds_read_b64_tr_b16 v[68:69], v188 offset:60416
	ds_read_b64_tr_b16 v[70:71], v188 offset:60928
	ds_read_b128 v[132:135], v168 offset:3072
	v_add_f32_e32 v140, v74, v144
	v_add_f32_e32 v140, v75, v140
	v_add_f32_e32 v140, v76, v140
	v_add_f32_e32 v140, v77, v140
	v_cvt_pk_bf16_f32 v144, v72, v73
	v_cvt_pk_bf16_f32 v145, v74, v75
	s_waitcnt lgkmcnt(0)
	v_mfma_f32_32x32x16_bf16 v[80:95], v[136:139], v[132:135], v[80:95]
	ds_read_b64_tr_b16 v[72:73], v188 offset:64512
	ds_read_b64_tr_b16 v[74:75], v188 offset:65024
	ds_read_b128 v[132:135], v168 offset:3072
	v_add_f32_e32 v136, v78, v140
	v_add_f32_e32 v136, v79, v136
	v_add_f32_e32 v136, 0, v136
	v_cvt_pk_bf16_f32 v146, v76, v77
	v_cvt_pk_bf16_f32 v147, v78, v79
	s_waitcnt lgkmcnt(0)
	v_mfma_f32_32x32x16_bf16 v[96:111], v[128:131], v[132:135], v[96:111]
	v_mfma_f32_32x32x16_bf16 v[48:63], v[156:159], v[170:173], v[48:63]
	ds_read_b64_tr_b16 v[76:77], v177 offset:40960
	ds_read_b64_tr_b16 v[78:79], v177 offset:41472
	v_exp_f32_e32 v80, v80
	v_exp_f32_e32 v81, v81
	v_mfma_f32_32x32x16_bf16 v[32:47], v[156:159], v[112:115], v[32:47]
	ds_read_b64_tr_b16 v[128:129], v177 offset:45056
	ds_read_b64_tr_b16 v[130:131], v177 offset:45568
	v_exp_f32_e32 v82, v82
	v_exp_f32_e32 v83, v83
	v_mfma_f32_32x32x16_bf16 v[48:63], v[152:155], v[116:119], v[48:63]
	ds_read_b64_tr_b16 v[112:113], v177 offset:41984
	ds_read_b64_tr_b16 v[114:115], v177 offset:42496
	v_exp_f32_e32 v84, v84
	v_exp_f32_e32 v85, v85
	v_mfma_f32_32x32x16_bf16 v[32:47], v[152:155], v[120:123], v[32:47]
	ds_read_b64_tr_b16 v[116:117], v177 offset:46080
	ds_read_b64_tr_b16 v[118:119], v177 offset:46592
	v_exp_f32_e32 v86, v86
	v_exp_f32_e32 v87, v87
	v_mfma_f32_32x32x16_bf16 v[48:63], v[148:151], v[124:127], v[48:63]
	ds_read_b64_tr_b16 v[120:121], v177 offset:43008
	ds_read_b64_tr_b16 v[122:123], v177 offset:43520
	v_exp_f32_e32 v88, v88
	v_exp_f32_e32 v89, v89
	v_mfma_f32_32x32x16_bf16 v[32:47], v[148:151], v[64:67], v[32:47]
	ds_read_b64_tr_b16 v[124:125], v177 offset:47104
	ds_read_b64_tr_b16 v[126:127], v177 offset:47616
	v_exp_f32_e32 v90, v90
	v_exp_f32_e32 v91, v91
	v_mfma_f32_32x32x16_bf16 v[48:63], v[144:147], v[68:71], v[48:63]
	ds_read_b64_tr_b16 v[64:65], v177 offset:44032
	ds_read_b64_tr_b16 v[66:67], v177 offset:44544
	v_exp_f32_e32 v92, v92
	v_exp_f32_e32 v93, v93
	v_mfma_f32_32x32x16_bf16 v[32:47], v[144:147], v[72:75], v[32:47]
	ds_read_b64_tr_b16 v[68:69], v177 offset:48128
	ds_read_b64_tr_b16 v[70:71], v177 offset:48640
	v_exp_f32_e32 v94, v94
	v_exp_f32_e32 v95, v95
	s_waitcnt lgkmcnt(14)
	v_mfma_f32_32x32x16_bf16 v[16:31], v[156:159], v[76:79], v[16:31]
	v_exp_f32_e32 v96, v96
	v_exp_f32_e32 v97, v97
	s_waitcnt lgkmcnt(12)
; #define SBAR() __builtin_amdgcn_sched_barrier(0)
; __device__ __forceinline__ void pv(f32x16*o,int vb,bf16x8 pa0,bf16x8 pa1,bf16x8 pa2,bf16x8 pa3){
;   #pragma unroll
;   for(int d0=0;d0<2;++d0){s16x4 lo[4],hi[4];
;     #pragma unroll
;     for(int ks=0;ks<4;++ks){
;       asm volatile("ds_read_b64_tr_b16 %0,%1 offset:%c2":"=&v"(lo[ks]):"v"(vb),"i"(d0*4096+ks*1024):"memory");
;       asm volatile("ds_read_b64_tr_b16 %0,%1 offset:%c2":"=&v"(hi[ks]):"v"(vb),"i"(d0*4096+ks*1024+512):"memory");}
;     asm volatile("s_waitcnt lgkmcnt(0)":::"memory");SBAR();
;     ...
;     o[d0]=__builtin_amdgcn_mfma_f32_32x32x16_bf16(pa0,PK(0),o[d0],0,0,0);
;     o[d0]=__builtin_amdgcn_mfma_f32_32x32x16_bf16(pa1,PK(1),o[d0],0,0,0);
;     o[d0]=__builtin_amdgcn_mfma_f32_32x32x16_bf16(pa2,PK(2),o[d0],0,0,0);
;     o[d0]=__builtin_amdgcn_mfma_f32_32x32x16_bf16(pa3,PK(3),o[d0],0,0,0);
;     ...
;   }
; }
; template<int THRL,int VM,bool NOMAX> __device__ __forceinline__ void attn_unit(const bf16*Qb,const bf16*__restrict__ Kh,const bf16*__restrict__ Vh,bf16*Ob,const int NT,const int sp,float*wscr,char*shm){
;     ...
;   int t=1;
;   for(;t+5<NT;t+=2){
;     STEP(pB0,pB1,pA0,pA1,t,true,true,true);     if constexpr(VM==2){WAIT_BAR(3);}else{WAIT_BAR(2);} RESC(); ROT();
;     STEP(pA0,pA1,pB0,pB1,t+1,true,true,true);   if constexpr(VM==2){WAIT_BAR(3);}else{WAIT_BAR(2);} RESC(); ROT();
;   }
;     ...
;   for(;t+1<NT;t+=2){
;     STEP(pB0,pB1,pA0,pA1,t,(t+3<NT),(t+1<NT),(t+1<NT));       ENDW(t);   RESC(); ROT();
;     STEP(pA0,pA1,pB0,pB1,t+1,(t+4<NT),(t+2<NT),(t+2<NT));     ENDW(t+1); RESC(); ROT();
;   }
;   STEP(pB0,pB1,pA0,pA1,NT-1,false,false,false); RESC();
;   { float sacc=pB0[0]+pB0[1]; _Pragma("unroll") for(int r=2;r<16;++r)sacc+=pB0[r]; _Pragma("unroll") for(int r=0;r<16;++r)sacc+=pB1[r]; l_reg+=sacc;
;     pw0=(u32x4){PKW(pB0,0),PKW(pB0,2),PKW(pB0,4),PKW(pB0,6)};pw1=(u32x4){PKW(pB0,8),PKW(pB0,10),PKW(pB0,12),PKW(pB0,14)};pw2=(u32x4){PKW(pB1,0),PKW(pB1,2),PKW(pB1,4),PKW(pB1,6)};pw3=(u32x4){PKW(pB1,8),PKW(pB1,10),PKW(pB1,12),PKW(pB1,14)};
;     SBAR(); pv(o,vb0+VM*sl_cur,PAF(0),PAF(1),PAF(2),PAF(3)); if constexpr(VM==2) pv(o+2,vb0+VM*sl_cur+8192,PAF(0),PAF(1),PAF(2),PAF(3)); }
;     ...
;   {auto rr=__builtin_amdgcn_permlane32_swap(__float_as_uint(l_reg),__float_as_uint(l_reg),false,false);l_reg=__uint_as_float(rr[0])+__uint_as_float(rr[1]);}
;   if(hi==0)wsf[32+r32]=l_reg;asm volatile("s_waitcnt lgkmcnt(0)":::"memory");
	v_mfma_f32_32x32x16_bf16 v[0:15], v[156:159], v[128:131], v[0:15]
	v_exp_f32_e32 v98, v98
	v_exp_f32_e32 v99, v99
	s_waitcnt lgkmcnt(10)
	v_mfma_f32_32x32x16_bf16 v[16:31], v[152:155], v[112:115], v[16:31]
	v_exp_f32_e32 v100, v100
	v_exp_f32_e32 v101, v101
	s_waitcnt lgkmcnt(8)
	v_mfma_f32_32x32x16_bf16 v[0:15], v[152:155], v[116:119], v[0:15]
	v_exp_f32_e32 v102, v102
	v_exp_f32_e32 v103, v103
	s_waitcnt lgkmcnt(6)
	v_mfma_f32_32x32x16_bf16 v[16:31], v[148:151], v[120:123], v[16:31]
	v_exp_f32_e32 v104, v104
	v_exp_f32_e32 v105, v105
	s_waitcnt lgkmcnt(4)
	v_mfma_f32_32x32x16_bf16 v[0:15], v[148:151], v[124:127], v[0:15]
	v_exp_f32_e32 v106, v106
	v_exp_f32_e32 v107, v107
	s_waitcnt lgkmcnt(2)
	v_mfma_f32_32x32x16_bf16 v[16:31], v[144:147], v[64:67], v[16:31]
	v_exp_f32_e32 v108, v108
	v_exp_f32_e32 v109, v109
	s_waitcnt lgkmcnt(0)
	v_mfma_f32_32x32x16_bf16 v[0:15], v[144:147], v[68:71], v[0:15]
	v_exp_f32_e32 v110, v110
	v_exp_f32_e32 v111, v111
	v_add_f32_e32 v64, v80, v81
	v_add_f32_e32 v64, v82, v64
	v_add_f32_e32 v64, v83, v64
	v_add_f32_e32 v64, v84, v64
	v_add_f32_e32 v64, v85, v64
	v_add_f32_e32 v64, v86, v64
	v_add_f32_e32 v64, v87, v64
	v_add_f32_e32 v64, v88, v64
	v_add_f32_e32 v64, v89, v64
	v_add_f32_e32 v64, v90, v64
	v_add_f32_e32 v64, v91, v64
	v_add_f32_e32 v64, v92, v64
	v_add_f32_e32 v64, v93, v64
	v_add_f32_e32 v64, v94, v64
	v_add_f32_e32 v64, v95, v64
	v_add_f32_e32 v64, v64, v96
	v_add_f32_e32 v64, v97, v64
	v_add_f32_e32 v64, v98, v64
	v_add_f32_e32 v64, v99, v64
	v_add_f32_e32 v64, v100, v64
	v_add_f32_e32 v64, v101, v64
	v_add_f32_e32 v64, v102, v64
	v_add_f32_e32 v64, v103, v64
	v_add_f32_e32 v64, v104, v64
	v_add_f32_e32 v64, v105, v64
	v_add_f32_e32 v64, v106, v64
	v_add_f32_e32 v64, v107, v64
	v_add_f32_e32 v64, v108, v64
	v_add_f32_e32 v64, v109, v64
	v_add_f32_e32 v64, v110, v64
	v_add_f32_e32 v64, v111, v64
	v_add_f32_e32 v65, v174, v136
	v_add_f32_e32 v64, v65, v64
	v_cvt_pk_bf16_f32 v66, v80, v81
	v_cvt_pk_bf16_f32 v67, v82, v83
	v_cvt_pk_bf16_f32 v68, v84, v85
	v_cvt_pk_bf16_f32 v69, v86, v87
	v_cvt_pk_bf16_f32 v70, v88, v89
	v_cvt_pk_bf16_f32 v71, v90, v91
	v_cvt_pk_bf16_f32 v72, v92, v93
	v_cvt_pk_bf16_f32 v73, v94, v95
	v_cvt_pk_bf16_f32 v74, v96, v97
	v_cvt_pk_bf16_f32 v75, v98, v99
	v_cvt_pk_bf16_f32 v76, v100, v101
	v_cvt_pk_bf16_f32 v77, v102, v103
	v_cvt_pk_bf16_f32 v78, v104, v105
	v_cvt_pk_bf16_f32 v79, v106, v107
	v_cvt_pk_bf16_f32 v80, v108, v109
	v_cvt_pk_bf16_f32 v81, v110, v111
	ds_read_b64_tr_b16 v[82:83],v176 offset:0
	ds_read_b64_tr_b16 v[84:85],v176 offset:512
	ds_read_b64_tr_b16 v[86:87],v176 offset:1024
	ds_read_b64_tr_b16 v[88:89],v176 offset:1536
	ds_read_b64_tr_b16 v[90:91],v176 offset:2048
	ds_read_b64_tr_b16 v[92:93],v176 offset:2560
	ds_read_b64_tr_b16 v[94:95],v176 offset:3072
	ds_read_b64_tr_b16 v[96:97],v176 offset:3584
	s_waitcnt lgkmcnt(0)
	s_nop 0
	v_mfma_f32_32x32x16_bf16 v[48:63], v[66:69], v[82:85], v[48:63]
	ds_read_b64_tr_b16 v[82:83],v176 offset:4096
	ds_read_b64_tr_b16 v[84:85],v176 offset:4608
	v_mfma_f32_32x32x16_bf16 v[48:63], v[70:73], v[86:89], v[48:63]
	ds_read_b64_tr_b16 v[86:87],v176 offset:5120
	ds_read_b64_tr_b16 v[88:89],v176 offset:5632
	v_mfma_f32_32x32x16_bf16 v[48:63], v[74:77], v[90:93], v[48:63]
	ds_read_b64_tr_b16 v[90:91],v176 offset:6144
	ds_read_b64_tr_b16 v[92:93],v176 offset:6656
	ds_read_b64_tr_b16 v[98:99],v176 offset:7168
	ds_read_b64_tr_b16 v[100:101],v176 offset:7680
	s_waitcnt lgkmcnt(0)
	v_mfma_f32_32x32x16_bf16 v[48:63], v[78:81], v[94:97], v[48:63]
	v_mfma_f32_32x32x16_bf16 v[32:47], v[66:69], v[82:85], v[32:47]
	v_add_u32_e32 v65, 0x2000, v176
	ds_read_b64_tr_b16 v[82:83],v65 offset:0
	ds_read_b64_tr_b16 v[84:85],v65 offset:512
	v_mfma_f32_32x32x16_bf16 v[32:47], v[70:73], v[86:89], v[32:47]
	ds_read_b64_tr_b16 v[86:87],v65 offset:1024
	ds_read_b64_tr_b16 v[88:89],v65 offset:1536
	v_mfma_f32_32x32x16_bf16 v[32:47], v[74:77], v[90:93], v[32:47]
	ds_read_b64_tr_b16 v[90:91],v65 offset:2048
	ds_read_b64_tr_b16 v[92:93],v65 offset:2560
	ds_read_b64_tr_b16 v[94:95],v65 offset:3072
	ds_read_b64_tr_b16 v[96:97],v65 offset:3584
	s_waitcnt lgkmcnt(0)
	v_mfma_f32_32x32x16_bf16 v[32:47], v[78:81], v[98:101], v[32:47]
	v_mfma_f32_32x32x16_bf16 v[16:31], v[66:69], v[82:85], v[16:31]
	ds_read_b64_tr_b16 v[82:83],v65 offset:4096
	ds_read_b64_tr_b16 v[84:85],v65 offset:4608
	v_mfma_f32_32x32x16_bf16 v[16:31], v[70:73], v[86:89], v[16:31]
	ds_read_b64_tr_b16 v[86:87],v65 offset:5120
	ds_read_b64_tr_b16 v[88:89],v65 offset:5632
	v_mfma_f32_32x32x16_bf16 v[16:31], v[74:77], v[90:93], v[16:31]
	ds_read_b64_tr_b16 v[90:91],v65 offset:6144
	ds_read_b64_tr_b16 v[92:93],v65 offset:6656
	ds_read_b64_tr_b16 v[98:99],v65 offset:7168
	ds_read_b64_tr_b16 v[100:101],v65 offset:7680
	s_waitcnt lgkmcnt(0)
	v_mfma_f32_32x32x16_bf16 v[16:31], v[78:81], v[94:97], v[16:31]
	v_mfma_f32_32x32x16_bf16 v[0:15], v[66:69], v[82:85], v[0:15]
	v_mov_b32_e32 v65, v64
	s_nop 1
	v_permlane32_swap_b32_e32 v64, v65
	v_cmp_gt_u32_e32 vcc, 32, v187
	v_mfma_f32_32x32x16_bf16 v[0:15], v[70:73], v[86:89], v[0:15]
	v_mfma_f32_32x32x16_bf16 v[0:15], v[74:77], v[90:93], v[0:15]
	v_mfma_f32_32x32x16_bf16 v[0:15], v[78:81], v[98:101], v[0:15]
	s_and_saveexec_b64 s[16:17], vcc
	s_cbranch_execz .LBB0_870
	v_add_f32_e32 v64, v64, v65
	v_lshl_add_u32 v65, v186, 2, s34
	ds_write_b32 v65, v64 offset:128
	s_branch .LBB0_870
